# GEMM MMA blocks acc-paired, pairs ordered so the first source operand is shared across 6 of 7 pair transitions
# baseline (speedup 1.0000x reference)
; #define PG8_STAGE(bufoff, gbase, voff) do { _Pragma("unroll") for (int _i = 0; _i < 2; ++_i) \
;         __builtin_amdgcn_global_load_lds((const unsigned*)((const char*)(gbase) + (voff)[_i]), (LAS unsigned*)(lds + (bufoff) + ldsw + _i * 8192), 16, 0, 0); } while (0)
; #define PG8_LDA(dst, b, h) do { _Pragma("unroll") for (int m = 0; m < 4; ++m) _Pragma("unroll") for (int k = 0; k < 2; ++k) dst[m][k] = *(const LAS bf16x8*)(lds + PG8_SA(b, h) + aoff + m * 2048 + k * 1024); } while (0)
; #define PG8_LDB(dst, b, h) do { _Pragma("unroll") for (int n = 0; n < 2; ++n) _Pragma("unroll") for (int k = 0; k < 2; ++k) dst[n][k] = *(const LAS bf16x8*)(lds + PG8_SB(b, h) + boff + n * 2048 + k * 1024); } while (0)
; #define PG8_MMA(ai, bj, At, Bt) do { __builtin_amdgcn_s_setprio(1); _Pragma("unroll") for (int m = 0; m < 4; ++m) _Pragma("unroll") for (int n = 0; n < 2; ++n) _Pragma("unroll") for (int k = 0; k < 2; ++k) \
;         acc[ai][bj][m][n] = __builtin_amdgcn_mfma_f32_16x16x32_bf16(Bt[n][k], At[m][k], acc[ai][bj][m][n], 0, 0, 0); __builtin_amdgcn_s_setprio(0); } while (0)
; #define PG8_WAIT_L(n) asm volatile("s_waitcnt lgkmcnt(" #n ")" ::: "memory")
; #define PG8_BAR __builtin_amdgcn_s_barrier()
; #define PG8_SCHED __builtin_amdgcn_sched_barrier(0)
; template <class Epi, class Ptrs>
; __device__ __forceinline__ void gemm_phase(LAS unsigned char* lds, const int K, const StaticOrder& S, const Ptrs& P, const Epi& E) {
;     ...
;         for (int t = 0; t < nt; t += 2) {
;             const bool last = (t == nt - 2);
;             const char* a1 = cA + (size_t)(t + 1) * kstep;
;             const char* a2 = last ? nA : cA + (size_t)(t + 2) * kstep; const char* b2 = last ? nB : cB + (size_t)(t + 2) * kstep;
;             const char* a3 = a2 + kstep; const char* b3 = b2 + kstep;
;             PG8_LDB(B0, 0, 0); PG8_SCHED; PG8_LDA(At, 0, 0); PG8_STAGE(PG8_SA(1, 1), a1 + hstep, voffA);
;             PG8_WAIT_L(8); PG8_BAR; PG8_WAIT_L(0); PG8_MMA(0, 0, At, B0); PG8_BAR; PG8_SCHED;
;             PG8_LDB(B1, 0, 1); PG8_STAGE(PG8_SB(0, 0), b2, voffB);
;             PG8_BAR; PG8_WAIT_L(0); PG8_MMA(0, 1, At, B1); PG8_BAR;
;             PG8_LDA(At, 0, 1); PG8_STAGE(PG8_SA(0, 0), a2, voffA);
;             PG8_BAR; PG8_WAIT_L(0); PG8_MMA(1, 0, At, B0); PG8_BAR; PG8_SCHED;
.LBB0_127:
	ds_read_b128 v[150:153], v205
	ds_read_b128 v[154:157], v205 offset:1024
	ds_read_b128 v[158:161], v205 offset:2048
	ds_read_b128 v[162:165], v205 offset:3072
	s_add_u32 s69, s6, 0xfffc0080
	s_addc_u32 s71, s7, -1
	s_cmp_eq_u32 s63, 12
	s_cselect_b32 s81, s1, s71
	s_cselect_b32 s80, s0, s69
	s_cselect_b32 s79, s73, s25
	s_cselect_b32 s78, s72, s20
	v_lshl_add_u64 v[198:199], s[6:7], 0, v[142:143]
	s_add_i32 m0, s67, 0xc000
	ds_read_b128 v[166:169], v206
	ds_read_b128 v[170:173], v206 offset:1024
	ds_read_b128 v[174:177], v206 offset:2048
	ds_read_b128 v[178:181], v206 offset:3072
	ds_read_b128 v[182:185], v206 offset:4096
	ds_read_b128 v[186:189], v206 offset:5120
	ds_read_b128 v[190:193], v206 offset:6144
	ds_read_b128 v[194:197], v206 offset:7168
	global_load_lds_dwordx4 v[198:199], off
	v_lshl_add_u64 v[198:199], s[6:7], 0, v[144:145]
	s_add_i32 m0, s67, 0xe000
	s_nop 0
	global_load_lds_dwordx4 v[198:199], off
	s_waitcnt lgkmcnt(8)
	s_barrier
	s_waitcnt lgkmcnt(0)
	s_setprio 1
	s_waitcnt lgkmcnt(0)
	v_mfma_f32_16x16x32_bf16 v[120:123], v[150:153], v[166:169], v[120:123]
	v_mfma_f32_16x16x32_bf16 v[120:123], v[154:157], v[170:173], v[120:123]
	v_mfma_f32_16x16x32_bf16 v[104:107], v[154:157], v[178:181], v[104:107]
	v_mfma_f32_16x16x32_bf16 v[104:107], v[150:153], v[174:177], v[104:107]
	v_mfma_f32_16x16x32_bf16 v[88:91], v[150:153], v[182:185], v[88:91]
	v_mfma_f32_16x16x32_bf16 v[88:91], v[154:157], v[186:189], v[88:91]
	v_mfma_f32_16x16x32_bf16 v[72:75], v[154:157], v[194:197], v[72:75]
	v_mfma_f32_16x16x32_bf16 v[72:75], v[150:153], v[190:193], v[72:75]
	v_mfma_f32_16x16x32_bf16 v[68:71], v[158:161], v[190:193], v[68:71]
	v_mfma_f32_16x16x32_bf16 v[68:71], v[162:165], v[194:197], v[68:71]
	v_mfma_f32_16x16x32_bf16 v[84:87], v[162:165], v[186:189], v[84:87]
	v_mfma_f32_16x16x32_bf16 v[84:87], v[158:161], v[182:185], v[84:87]
	v_mfma_f32_16x16x32_bf16 v[100:103], v[158:161], v[174:177], v[100:103]
	v_mfma_f32_16x16x32_bf16 v[100:103], v[162:165], v[178:181], v[100:103]
	v_mfma_f32_16x16x32_bf16 v[116:119], v[162:165], v[170:173], v[116:119]
	v_mfma_f32_16x16x32_bf16 v[116:119], v[158:161], v[166:169], v[116:119]
	s_setprio 0
	s_barrier
	s_add_i32 s69, s91, s65
	v_lshl_add_u64 v[202:203], s[78:79], 0, v[134:135]
	s_mov_b32 m0, s69
	ds_read_b128 v[198:201], v207
	ds_read_b128 v[210:213], v207 offset:1024
	ds_read_b128 v[214:217], v207 offset:2048
	ds_read_b128 v[218:221], v207 offset:3072
	global_load_lds_dwordx4 v[202:203], off
	v_lshl_add_u64 v[222:223], s[78:79], 0, v[138:139]
	s_add_i32 m0, s69, 0x2000
	s_nop 0
	global_load_lds_dwordx4 v[222:223], off
	s_barrier
	s_waitcnt lgkmcnt(0)
	s_setprio 1
	s_waitcnt lgkmcnt(0)
	v_mfma_f32_16x16x32_bf16 v[124:127], v[198:201], v[166:169], v[124:127]
	v_mfma_f32_16x16x32_bf16 v[124:127], v[210:213], v[170:173], v[124:127]
	v_mfma_f32_16x16x32_bf16 v[108:111], v[210:213], v[178:181], v[108:111]
	v_mfma_f32_16x16x32_bf16 v[108:111], v[198:201], v[174:177], v[108:111]
	v_mfma_f32_16x16x32_bf16 v[92:95], v[198:201], v[182:185], v[92:95]
	v_mfma_f32_16x16x32_bf16 v[92:95], v[210:213], v[186:189], v[92:95]
	v_mfma_f32_16x16x32_bf16 v[76:79], v[210:213], v[194:197], v[76:79]
	v_mfma_f32_16x16x32_bf16 v[76:79], v[198:201], v[190:193], v[76:79]
	v_mfma_f32_16x16x32_bf16 v[64:67], v[214:217], v[190:193], v[64:67]
	v_mfma_f32_16x16x32_bf16 v[64:67], v[218:221], v[194:197], v[64:67]
	v_mfma_f32_16x16x32_bf16 v[80:83], v[218:221], v[186:189], v[80:83]
	v_mfma_f32_16x16x32_bf16 v[80:83], v[214:217], v[182:185], v[80:83]
	v_mfma_f32_16x16x32_bf16 v[96:99], v[214:217], v[174:177], v[96:99]
	v_mfma_f32_16x16x32_bf16 v[96:99], v[218:221], v[178:181], v[96:99]
	v_mfma_f32_16x16x32_bf16 v[112:115], v[218:221], v[170:173], v[112:115]
	v_mfma_f32_16x16x32_bf16 v[112:115], v[214:217], v[166:169], v[112:115]
	s_setprio 0
	s_mov_b32 m0, s67
	v_lshl_add_u64 v[224:225], s[80:81], 0, v[132:133]
	s_barrier
	ds_read_b128 v[166:169], v206 offset:16384
	ds_read_b128 v[170:173], v206 offset:17408
	ds_read_b128 v[174:177], v206 offset:18432
	ds_read_b128 v[178:181], v206 offset:19456
	ds_read_b128 v[182:185], v206 offset:20480
	ds_read_b128 v[186:189], v206 offset:21504
	ds_read_b128 v[190:193], v206 offset:22528
	ds_read_b128 v[194:197], v206 offset:23552
	global_load_lds_dwordx4 v[224:225], off
	v_lshl_add_u64 v[226:227], s[80:81], 0, v[136:137]
	s_mov_b32 m0, s75
	s_nop 0
	global_load_lds_dwordx4 v[226:227], off
	s_barrier
	s_waitcnt lgkmcnt(0)
	s_setprio 1
	s_waitcnt lgkmcnt(0)
	v_mfma_f32_16x16x32_bf16 v[56:59], v[150:153], v[166:169], v[56:59]
	v_mfma_f32_16x16x32_bf16 v[56:59], v[154:157], v[170:173], v[56:59]
	v_mfma_f32_16x16x32_bf16 v[40:43], v[154:157], v[178:181], v[40:43]
	v_mfma_f32_16x16x32_bf16 v[40:43], v[150:153], v[174:177], v[40:43]
	v_mfma_f32_16x16x32_bf16 v[24:27], v[150:153], v[182:185], v[24:27]
	v_mfma_f32_16x16x32_bf16 v[24:27], v[154:157], v[186:189], v[24:27]
	v_mfma_f32_16x16x32_bf16 v[8:11], v[154:157], v[194:197], v[8:11]
	v_mfma_f32_16x16x32_bf16 v[8:11], v[150:153], v[190:193], v[8:11]
	v_mfma_f32_16x16x32_bf16 v[4:7], v[158:161], v[190:193], v[4:7]
	v_mfma_f32_16x16x32_bf16 v[4:7], v[162:165], v[194:197], v[4:7]
	v_mfma_f32_16x16x32_bf16 v[20:23], v[162:165], v[186:189], v[20:23]
	v_mfma_f32_16x16x32_bf16 v[20:23], v[158:161], v[182:185], v[20:23]
	v_mfma_f32_16x16x32_bf16 v[36:39], v[158:161], v[174:177], v[36:39]
	v_mfma_f32_16x16x32_bf16 v[36:39], v[162:165], v[178:181], v[36:39]
	v_mfma_f32_16x16x32_bf16 v[52:55], v[162:165], v[170:173], v[52:55]
	v_mfma_f32_16x16x32_bf16 v[52:55], v[158:161], v[166:169], v[52:55]
	s_setprio 0
	s_barrier
; #define PG8_STAGE(bufoff, gbase, voff) do { _Pragma("unroll") for (int _i = 0; _i < 2; ++_i) \
;         __builtin_amdgcn_global_load_lds((const unsigned*)((const char*)(gbase) + (voff)[_i]), (LAS unsigned*)(lds + (bufoff) + ldsw + _i * 8192), 16, 0, 0); } while (0)
; #define PG8_LDA(dst, b, h) do { _Pragma("unroll") for (int m = 0; m < 4; ++m) _Pragma("unroll") for (int k = 0; k < 2; ++k) dst[m][k] = *(const LAS bf16x8*)(lds + PG8_SA(b, h) + aoff + m * 2048 + k * 1024); } while (0)
; #define PG8_LDB(dst, b, h) do { _Pragma("unroll") for (int n = 0; n < 2; ++n) _Pragma("unroll") for (int k = 0; k < 2; ++k) dst[n][k] = *(const LAS bf16x8*)(lds + PG8_SB(b, h) + boff + n * 2048 + k * 1024); } while (0)
; #define PG8_MMA(ai, bj, At, Bt) do { __builtin_amdgcn_s_setprio(1); _Pragma("unroll") for (int m = 0; m < 4; ++m) _Pragma("unroll") for (int n = 0; n < 2; ++n) _Pragma("unroll") for (int k = 0; k < 2; ++k) \
;         acc[ai][bj][m][n] = __builtin_amdgcn_mfma_f32_16x16x32_bf16(Bt[n][k], At[m][k], acc[ai][bj][m][n], 0, 0, 0); __builtin_amdgcn_s_setprio(0); } while (0)
; #define PG8_WAIT_V(n) asm volatile("s_waitcnt vmcnt(" #n ")" ::: "memory")
; #define PG8_WAIT_L(n) asm volatile("s_waitcnt lgkmcnt(" #n ")" ::: "memory")
; #define PG8_BAR __builtin_amdgcn_s_barrier()
; #define PG8_SCHED __builtin_amdgcn_sched_barrier(0)
; template <class Epi, class Ptrs>
; __device__ __forceinline__ void gemm_phase(LAS unsigned char* lds, const int K, const StaticOrder& S, const Ptrs& P, const Epi& E) {
;     ...
;             PG8_STAGE(PG8_SB(0, 1), b2 + hstep, voffB);
;             PG8_WAIT_V(6); PG8_BAR; PG8_MMA(1, 1, At, B1); PG8_BAR;
;             PG8_LDB(B0, 1, 0); PG8_SCHED; PG8_LDA(At, 1, 0); PG8_STAGE(PG8_SA(0, 1), a2 + hstep, voffA);
;             PG8_WAIT_L(8); PG8_BAR; PG8_WAIT_L(0); PG8_MMA(0, 0, At, B0); PG8_BAR; PG8_SCHED;
	s_add_u32 s82, s78, 0x40000
	s_addc_u32 s83, s79, 0
	s_add_i32 s69, s92, s65
	v_lshl_add_u64 v[150:151], s[82:83], 0, v[134:135]
	s_mov_b32 m0, s69
	s_nop 0
	global_load_lds_dwordx4 v[150:151], off
	v_lshl_add_u64 v[150:151], s[82:83], 0, v[138:139]
	s_add_i32 m0, s69, 0x2000
	s_nop 0
	global_load_lds_dwordx4 v[150:151], off
	s_waitcnt vmcnt(6)
	s_barrier
	s_setprio 1
	v_mfma_f32_16x16x32_bf16 v[60:63], v[198:201], v[166:169], v[60:63]
	v_mfma_f32_16x16x32_bf16 v[60:63], v[210:213], v[170:173], v[60:63]
	v_mfma_f32_16x16x32_bf16 v[44:47], v[210:213], v[178:181], v[44:47]
	v_mfma_f32_16x16x32_bf16 v[44:47], v[198:201], v[174:177], v[44:47]
	v_mfma_f32_16x16x32_bf16 v[28:31], v[198:201], v[182:185], v[28:31]
	v_mfma_f32_16x16x32_bf16 v[28:31], v[210:213], v[186:189], v[28:31]
	v_mfma_f32_16x16x32_bf16 v[12:15], v[210:213], v[194:197], v[12:15]
	v_mfma_f32_16x16x32_bf16 v[12:15], v[198:201], v[190:193], v[12:15]
	v_mfma_f32_16x16x32_bf16 v[0:3], v[214:217], v[190:193], v[0:3]
	v_mfma_f32_16x16x32_bf16 v[0:3], v[218:221], v[194:197], v[0:3]
	v_mfma_f32_16x16x32_bf16 v[16:19], v[218:221], v[186:189], v[16:19]
	v_mfma_f32_16x16x32_bf16 v[16:19], v[214:217], v[182:185], v[16:19]
	v_mfma_f32_16x16x32_bf16 v[32:35], v[214:217], v[174:177], v[32:35]
	v_mfma_f32_16x16x32_bf16 v[32:35], v[218:221], v[178:181], v[32:35]
	v_mfma_f32_16x16x32_bf16 v[48:51], v[218:221], v[170:173], v[48:51]
	v_mfma_f32_16x16x32_bf16 v[48:51], v[214:217], v[166:169], v[48:51]
	s_setprio 0
	s_add_i32 s69, 0, 0x18000
	v_add_u32_e32 v140, s69, v131
	s_barrier
	ds_read_b128 v[150:153], v140
	ds_read_b128 v[154:157], v140 offset:1024
	ds_read_b128 v[158:161], v140 offset:2048
	ds_read_b128 v[162:165], v140 offset:3072
	s_add_u32 s80, s80, 0x40000
	s_addc_u32 s81, s81, 0
	s_mov_b32 m0, s77
	v_lshl_add_u64 v[198:199], s[80:81], 0, v[132:133]
	ds_read_b128 v[166:169], v206 offset:32768
	ds_read_b128 v[170:173], v206 offset:33792
	ds_read_b128 v[174:177], v206 offset:34816
	ds_read_b128 v[178:181], v206 offset:35840
	ds_read_b128 v[182:185], v206 offset:36864
	ds_read_b128 v[186:189], v206 offset:37888
	ds_read_b128 v[190:193], v206 offset:38912
	ds_read_b128 v[194:197], v206 offset:39936
	global_load_lds_dwordx4 v[198:199], off
	v_lshl_add_u64 v[198:199], s[80:81], 0, v[136:137]
	s_mov_b32 m0, s85
	s_nop 0
	global_load_lds_dwordx4 v[198:199], off
	s_waitcnt lgkmcnt(8)
	s_barrier
	s_waitcnt lgkmcnt(0)
	s_setprio 1
	s_waitcnt lgkmcnt(0)
	v_mfma_f32_16x16x32_bf16 v[120:123], v[150:153], v[166:169], v[120:123]
	v_mfma_f32_16x16x32_bf16 v[120:123], v[154:157], v[170:173], v[120:123]
	v_mfma_f32_16x16x32_bf16 v[104:107], v[154:157], v[178:181], v[104:107]
	v_mfma_f32_16x16x32_bf16 v[104:107], v[150:153], v[174:177], v[104:107]
	v_mfma_f32_16x16x32_bf16 v[88:91], v[150:153], v[182:185], v[88:91]
	v_mfma_f32_16x16x32_bf16 v[88:91], v[154:157], v[186:189], v[88:91]
	v_mfma_f32_16x16x32_bf16 v[72:75], v[154:157], v[194:197], v[72:75]
	v_mfma_f32_16x16x32_bf16 v[72:75], v[150:153], v[190:193], v[72:75]
	v_mfma_f32_16x16x32_bf16 v[68:71], v[158:161], v[190:193], v[68:71]
	v_mfma_f32_16x16x32_bf16 v[68:71], v[162:165], v[194:197], v[68:71]
	v_mfma_f32_16x16x32_bf16 v[84:87], v[162:165], v[186:189], v[84:87]
	v_mfma_f32_16x16x32_bf16 v[84:87], v[158:161], v[182:185], v[84:87]
	v_mfma_f32_16x16x32_bf16 v[100:103], v[158:161], v[174:177], v[100:103]
	v_mfma_f32_16x16x32_bf16 v[100:103], v[162:165], v[178:181], v[100:103]
	v_mfma_f32_16x16x32_bf16 v[116:119], v[162:165], v[170:173], v[116:119]
	v_mfma_f32_16x16x32_bf16 v[116:119], v[158:161], v[166:169], v[116:119]
	s_setprio 0
	s_barrier
	s_add_i32 s71, 0, 0x1c000
	s_add_i32 s69, s69, s65
	v_add_u32_e32 v140, s71, v131
	v_lshl_add_u64 v[202:203], v[202:203], 0, s[58:59]
	s_mov_b32 m0, s69
	ds_read_b128 v[198:201], v140
	ds_read_b128 v[210:213], v140 offset:1024
	ds_read_b128 v[214:217], v140 offset:2048
	ds_read_b128 v[218:221], v140 offset:3072
	global_load_lds_dwordx4 v[202:203], off
	v_lshl_add_u64 v[202:203], v[222:223], 0, s[58:59]
	s_add_i32 m0, s69, 0x2000
	s_nop 0
	global_load_lds_dwordx4 v[202:203], off
	s_barrier
; #define PG8_WAIT_V(n) asm volatile("s_waitcnt vmcnt(" #n ")" ::: "memory")
; template <class Epi, class Ptrs>
; __device__ __forceinline__ void gemm_phase(LAS unsigned char* lds, const int K, const StaticOrder& S, const Ptrs& P, const Epi& E) {
;     ...
;             PG8_BAR; PG8_WAIT_L(0); PG8_MMA(0, 1, At, B1); PG8_BAR;
;             PG8_LDA(At, 1, 1); PG8_STAGE(PG8_SA(1, 0), a3, voffA);
;             PG8_BAR; PG8_WAIT_L(0); PG8_MMA(1, 0, At, B0); PG8_BAR; PG8_SCHED;
;             PG8_STAGE(PG8_SB(1, 1), b3 + hstep, voffB);
;             PG8_WAIT_V(6); PG8_BAR; PG8_MMA(1, 1, At, B1); PG8_BAR;
;     __device__ __forceinline__ void operator()(const f32x4 (&acc)[2][2][4][2], const Unit& u, int ui, int wr, int wc, int fr, int fq) const {
;         const int pn = u.pn;
;         if (pn < 8) {
;             bf16_t* base = (bf16_t*)(ws + WS_U) + (size_t)(u.pm * 256 + wr * 64 + fr) * DM + pn * 128 + wc * 32 + 8 * fq;
; #pragma unroll
;             for (int ai = 0; ai < 2; ++ai)
; #pragma unroll
;                 for (int m = 0; m < 4; ++m) {
;                     const f32x4 g0 = g1_4(acc[ai][0][m][0], acc[ai][1][m][0]), g1 = g1_4(acc[ai][0][m][1], acc[ai][1][m][1]);
;                     *(u32x4*)(base + (size_t)(ai * 128 + m * 16) * DM) = pack8(g0, g1); }
;             return; }
;         if (pn >= 17 && pn < 21) {
;             bf16_t* base = (bf16_t*)(dout + DO_GVT) + (size_t)((pn - 17) * 256 + wr * 64 + fr) * MTOK + u.pm * 256 + wc * 32 + 8 * fq;
;             float* pp = (float*)(ws + WS_PART) + (size_t)(u.pm * 256 + wc * 32 + 8 * fq) * 8 + (pn - 17) * 2 + wr;
; #pragma unroll
;             for (int bj = 0; bj < 2; ++bj) { f32x4 sq0 = {0.f, 0.f, 0.f, 0.f}, sq1 = {0.f, 0.f, 0.f, 0.f};
; #pragma unroll
;                 for (int ai = 0; ai < 2; ++ai)
; #pragma unroll
;                     for (int m = 0; m < 4; ++m) { const f32x4 g0 = gelu4(acc[ai][bj][m][0]), g1 = gelu4(acc[ai][bj][m][1]);
;                         sq0 += g0 * g0; sq1 += g1 * g1;
;                         *(u32x4*)(base + (size_t)(ai * 128 + m * 16) * MTOK + bj * 128) = pack8(g0, g1); }
; #pragma unroll
;                 for (int j = 0; j < 4; ++j) { const float t0 = row16_sum(sq0[j]), t1 = row16_sum(sq1[j]); if (fr == 0) { pp[(size_t)(bj * 128 + j) * 8] = t0; pp[(size_t)(bj * 128 + 4 + j) * 8] = t1; } } }
;             return; }
;         bf16_t* base; size_t ld; int row0, col0, act;
	s_waitcnt lgkmcnt(0)
	s_setprio 1
	s_waitcnt lgkmcnt(0)
	v_mfma_f32_16x16x32_bf16 v[124:127], v[198:201], v[166:169], v[124:127]
	v_mfma_f32_16x16x32_bf16 v[124:127], v[210:213], v[170:173], v[124:127]
	v_mfma_f32_16x16x32_bf16 v[108:111], v[210:213], v[178:181], v[108:111]
	v_mfma_f32_16x16x32_bf16 v[108:111], v[198:201], v[174:177], v[108:111]
	v_mfma_f32_16x16x32_bf16 v[92:95], v[198:201], v[182:185], v[92:95]
	v_mfma_f32_16x16x32_bf16 v[92:95], v[210:213], v[186:189], v[92:95]
	v_mfma_f32_16x16x32_bf16 v[76:79], v[210:213], v[194:197], v[76:79]
	v_mfma_f32_16x16x32_bf16 v[76:79], v[198:201], v[190:193], v[76:79]
	v_mfma_f32_16x16x32_bf16 v[64:67], v[214:217], v[190:193], v[64:67]
	v_mfma_f32_16x16x32_bf16 v[64:67], v[218:221], v[194:197], v[64:67]
	v_mfma_f32_16x16x32_bf16 v[80:83], v[218:221], v[186:189], v[80:83]
	v_mfma_f32_16x16x32_bf16 v[80:83], v[214:217], v[182:185], v[80:83]
	v_mfma_f32_16x16x32_bf16 v[96:99], v[214:217], v[174:177], v[96:99]
	v_mfma_f32_16x16x32_bf16 v[96:99], v[218:221], v[178:181], v[96:99]
	v_mfma_f32_16x16x32_bf16 v[112:115], v[218:221], v[170:173], v[112:115]
	v_mfma_f32_16x16x32_bf16 v[112:115], v[214:217], v[166:169], v[112:115]
	s_setprio 0
	s_mov_b32 m0, s89
	v_lshl_add_u64 v[202:203], v[224:225], 0, s[58:59]
	s_barrier
	ds_read_b128 v[166:169], v206 offset:49152
	ds_read_b128 v[170:173], v206 offset:50176
	ds_read_b128 v[174:177], v206 offset:51200
	ds_read_b128 v[178:181], v206 offset:52224
	ds_read_b128 v[182:185], v206 offset:53248
	ds_read_b128 v[186:189], v206 offset:54272
	ds_read_b128 v[190:193], v206 offset:55296
	ds_read_b128 v[194:197], v206 offset:56320
	global_load_lds_dwordx4 v[202:203], off
	v_lshl_add_u64 v[202:203], v[226:227], 0, s[58:59]
	s_mov_b32 m0, s90
	s_nop 0
	global_load_lds_dwordx4 v[202:203], off
	s_barrier
	s_waitcnt lgkmcnt(0)
	s_setprio 1
	s_waitcnt lgkmcnt(0)
	v_mfma_f32_16x16x32_bf16 v[56:59], v[150:153], v[166:169], v[56:59]
	v_mfma_f32_16x16x32_bf16 v[56:59], v[154:157], v[170:173], v[56:59]
	v_mfma_f32_16x16x32_bf16 v[40:43], v[154:157], v[178:181], v[40:43]
	v_mfma_f32_16x16x32_bf16 v[40:43], v[150:153], v[174:177], v[40:43]
	v_mfma_f32_16x16x32_bf16 v[24:27], v[150:153], v[182:185], v[24:27]
	v_mfma_f32_16x16x32_bf16 v[24:27], v[154:157], v[186:189], v[24:27]
	v_mfma_f32_16x16x32_bf16 v[8:11], v[154:157], v[194:197], v[8:11]
	v_mfma_f32_16x16x32_bf16 v[8:11], v[150:153], v[190:193], v[8:11]
	v_mfma_f32_16x16x32_bf16 v[4:7], v[158:161], v[190:193], v[4:7]
	v_mfma_f32_16x16x32_bf16 v[4:7], v[162:165], v[194:197], v[4:7]
	v_mfma_f32_16x16x32_bf16 v[20:23], v[162:165], v[186:189], v[20:23]
	v_mfma_f32_16x16x32_bf16 v[20:23], v[158:161], v[182:185], v[20:23]
	v_mfma_f32_16x16x32_bf16 v[36:39], v[158:161], v[174:177], v[36:39]
	v_mfma_f32_16x16x32_bf16 v[36:39], v[162:165], v[178:181], v[36:39]
	v_mfma_f32_16x16x32_bf16 v[52:55], v[162:165], v[170:173], v[52:55]
	v_mfma_f32_16x16x32_bf16 v[52:55], v[158:161], v[166:169], v[52:55]
	s_setprio 0
	s_barrier
	s_add_u32 s78, s78, 0x40080
	s_addc_u32 s79, s79, 0
	s_add_i32 s69, s71, s65
	v_lshl_add_u64 v[150:151], s[78:79], 0, v[134:135]
	s_mov_b32 m0, s69
	s_nop 0
	global_load_lds_dwordx4 v[150:151], off
	v_lshl_add_u64 v[150:151], s[78:79], 0, v[138:139]
	s_add_i32 m0, s69, 0x2000
	s_nop 0
	global_load_lds_dwordx4 v[150:151], off
	s_waitcnt vmcnt(6)
	s_barrier
	s_setprio 1
	v_mfma_f32_16x16x32_bf16 v[60:63], v[198:201], v[166:169], v[60:63]
	v_mfma_f32_16x16x32_bf16 v[60:63], v[210:213], v[170:173], v[60:63]
	v_mfma_f32_16x16x32_bf16 v[44:47], v[210:213], v[178:181], v[44:47]
	v_mfma_f32_16x16x32_bf16 v[44:47], v[198:201], v[174:177], v[44:47]
	v_mfma_f32_16x16x32_bf16 v[28:31], v[198:201], v[182:185], v[28:31]
	v_mfma_f32_16x16x32_bf16 v[28:31], v[210:213], v[186:189], v[28:31]
	v_mfma_f32_16x16x32_bf16 v[12:15], v[210:213], v[194:197], v[12:15]
	v_mfma_f32_16x16x32_bf16 v[12:15], v[198:201], v[190:193], v[12:15]
	v_mfma_f32_16x16x32_bf16 v[0:3], v[214:217], v[190:193], v[0:3]
	v_mfma_f32_16x16x32_bf16 v[0:3], v[218:221], v[194:197], v[0:3]
	v_mfma_f32_16x16x32_bf16 v[16:19], v[218:221], v[186:189], v[16:19]
	v_mfma_f32_16x16x32_bf16 v[16:19], v[214:217], v[182:185], v[16:19]
	v_mfma_f32_16x16x32_bf16 v[32:35], v[214:217], v[174:177], v[32:35]
	v_mfma_f32_16x16x32_bf16 v[32:35], v[218:221], v[178:181], v[32:35]
	v_mfma_f32_16x16x32_bf16 v[48:51], v[218:221], v[170:173], v[48:51]
	v_mfma_f32_16x16x32_bf16 v[48:51], v[214:217], v[166:169], v[48:51]
	s_setprio 0
	s_add_i32 s63, s63, 2
	s_add_u32 s6, s6, 0x100
	s_addc_u32 s7, s7, 0
	s_add_u32 s20, s20, 0x100
	s_addc_u32 s25, s25, 0
	s_cmp_gt_u32 s63, 13
	s_barrier
	s_cbranch_scc0 .LBB0_127
	s_cmp_gt_i32 s74, 7
	s_mov_b64 s[6:7], -1
	s_cbranch_scc0 .LBB0_188
	s_sub_i32 s25, s74, 17
	s_cmp_gt_u32 s25, 3
	s_cbranch_scc0 .LBB0_170
	s_lshl_b32 s69, s76, 8
	s_cmp_gt_u32 s74, 11
	s_cbranch_scc0 .LBB0_135
	s_cmp_eq_u32 s74, 12
	s_mov_b64 s[6:7], 0
	s_cbranch_scc1 .LBB0_134
	s_cmp_gt_u32 s74, 16
	s_cbranch_scc1 .LBB0_191
	s_lshl_b32 s20, s74, 8
	v_readlane_b32 s80, v254, 2
	s_addk_i32 s20, 0xf300
	s_mov_b64 s[78:79], 0x400
	s_mov_b64 s[82:83], -1
	s_mov_b32 s63, s69
	v_readlane_b32 s81, v254, 3
	s_andn2_b64 vcc, exec, s[6:7]
	s_cbranch_vccz .LBB0_136
	s_branch .LBB0_137

; #define PG8_STAGE(bufoff, gbase, voff) do { _Pragma("unroll") for (int _i = 0; _i < 2; ++_i) \
;         __builtin_amdgcn_global_load_lds((const unsigned*)((const char*)(gbase) + (voff)[_i]), (LAS unsigned*)(lds + (bufoff) + ldsw + _i * 8192), 16, 0, 0); } while (0)
; #define PG8_LDA(dst, b, h) do { _Pragma("unroll") for (int m = 0; m < 4; ++m) _Pragma("unroll") for (int k = 0; k < 2; ++k) dst[m][k] = *(const LAS bf16x8*)(lds + PG8_SA(b, h) + aoff + m * 2048 + k * 1024); } while (0)
; #define PG8_LDB(dst, b, h) do { _Pragma("unroll") for (int n = 0; n < 2; ++n) _Pragma("unroll") for (int k = 0; k < 2; ++k) dst[n][k] = *(const LAS bf16x8*)(lds + PG8_SB(b, h) + boff + n * 2048 + k * 1024); } while (0)
; #define PG8_MMA(ai, bj, At, Bt) do { __builtin_amdgcn_s_setprio(1); _Pragma("unroll") for (int m = 0; m < 4; ++m) _Pragma("unroll") for (int n = 0; n < 2; ++n) _Pragma("unroll") for (int k = 0; k < 2; ++k) \
;         acc[ai][bj][m][n] = __builtin_amdgcn_mfma_f32_16x16x32_bf16(Bt[n][k], At[m][k], acc[ai][bj][m][n], 0, 0, 0); __builtin_amdgcn_s_setprio(0); } while (0)
; #define PG8_WAIT_L(n) asm volatile("s_waitcnt lgkmcnt(" #n ")" ::: "memory")
; #define PG8_BAR __builtin_amdgcn_s_barrier()
; #define PG8_SCHED __builtin_amdgcn_sched_barrier(0)
; template <class Epi, class Ptrs>
; __device__ __forceinline__ void gemm_phase(LAS unsigned char* lds, const int K, const StaticOrder& S, const Ptrs& P, const Epi& E) {
;     ...
;         for (int t = 0; t < nt; t += 2) {
;             const bool last = (t == nt - 2);
;             const char* a1 = cA + (size_t)(t + 1) * kstep;
;             const char* a2 = last ? nA : cA + (size_t)(t + 2) * kstep; const char* b2 = last ? nB : cB + (size_t)(t + 2) * kstep;
;             const char* a3 = a2 + kstep; const char* b3 = b2 + kstep;
;             PG8_LDB(B0, 0, 0); PG8_SCHED; PG8_LDA(At, 0, 0); PG8_STAGE(PG8_SA(1, 1), a1 + hstep, voffA);
;             PG8_WAIT_L(8); PG8_BAR; PG8_WAIT_L(0); PG8_MMA(0, 0, At, B0); PG8_BAR; PG8_SCHED;
;             PG8_LDB(B1, 0, 1); PG8_STAGE(PG8_SB(0, 0), b2, voffB);
;             PG8_BAR; PG8_WAIT_L(0); PG8_MMA(0, 1, At, B1); PG8_BAR;
;             PG8_LDA(At, 0, 1); PG8_STAGE(PG8_SA(0, 0), a2, voffA);
;             PG8_BAR; PG8_WAIT_L(0); PG8_MMA(1, 0, At, B0); PG8_BAR; PG8_SCHED;
.LBB0_353:
	ds_read_b128 v[128:131], v207
	ds_read_b128 v[132:135], v207 offset:1024
	ds_read_b128 v[136:139], v207 offset:2048
	ds_read_b128 v[140:143], v207 offset:3072
	s_add_u32 s42, s38, 0xfffc0080
	s_addc_u32 s43, s39, -1
	s_cmp_eq_u32 s41, 12
	s_cselect_b32 s45, s1, s43
	s_cselect_b32 s44, s0, s42
	s_cselect_b32 s43, s25, s23
	s_cselect_b32 s42, s24, s21
	v_lshl_add_u64 v[192:193], s[38:39], 0, v[184:185]
	s_add_i32 m0, s54, 0xc000
	ds_read_b128 v[144:147], v209
	ds_read_b128 v[148:151], v209 offset:1024
	ds_read_b128 v[152:155], v209 offset:2048
	ds_read_b128 v[156:159], v209 offset:3072
	ds_read_b128 v[160:163], v209 offset:4096
	ds_read_b128 v[164:167], v209 offset:5120
	ds_read_b128 v[168:171], v209 offset:6144
	ds_read_b128 v[172:175], v209 offset:7168
	global_load_lds_dwordx4 v[192:193], off
	v_lshl_add_u64 v[192:193], s[38:39], 0, v[186:187]
	s_add_i32 m0, s54, 0xe000
	s_nop 0
	global_load_lds_dwordx4 v[192:193], off
	s_waitcnt lgkmcnt(8)
	s_barrier
	s_waitcnt lgkmcnt(0)
	s_setprio 1
	s_waitcnt lgkmcnt(0)
	v_mfma_f32_16x16x32_bf16 v[124:127], v[128:131], v[144:147], v[124:127]
	v_mfma_f32_16x16x32_bf16 v[124:127], v[132:135], v[148:151], v[124:127]
	v_mfma_f32_16x16x32_bf16 v[108:111], v[132:135], v[156:159], v[108:111]
	v_mfma_f32_16x16x32_bf16 v[108:111], v[128:131], v[152:155], v[108:111]
	v_mfma_f32_16x16x32_bf16 v[92:95], v[128:131], v[160:163], v[92:95]
	v_mfma_f32_16x16x32_bf16 v[92:95], v[132:135], v[164:167], v[92:95]
	v_mfma_f32_16x16x32_bf16 v[76:79], v[132:135], v[172:175], v[76:79]
	v_mfma_f32_16x16x32_bf16 v[76:79], v[128:131], v[168:171], v[76:79]
	v_mfma_f32_16x16x32_bf16 v[72:75], v[136:139], v[168:171], v[72:75]
	v_mfma_f32_16x16x32_bf16 v[72:75], v[140:143], v[172:175], v[72:75]
	v_mfma_f32_16x16x32_bf16 v[88:91], v[140:143], v[164:167], v[88:91]
	v_mfma_f32_16x16x32_bf16 v[88:91], v[136:139], v[160:163], v[88:91]
	v_mfma_f32_16x16x32_bf16 v[104:107], v[136:139], v[152:155], v[104:107]
	v_mfma_f32_16x16x32_bf16 v[104:107], v[140:143], v[156:159], v[104:107]
	v_mfma_f32_16x16x32_bf16 v[120:123], v[140:143], v[148:151], v[120:123]
	v_mfma_f32_16x16x32_bf16 v[120:123], v[136:139], v[144:147], v[120:123]
	s_setprio 0
	s_barrier
	s_add_i32 s69, s66, s51
	v_lshl_add_u64 v[216:217], s[42:43], 0, v[178:179]
	s_mov_b32 m0, s69
	ds_read_b128 v[192:195], v210
	ds_read_b128 v[196:199], v210 offset:1024
	ds_read_b128 v[200:203], v210 offset:2048
	ds_read_b128 v[212:215], v210 offset:3072
	global_load_lds_dwordx4 v[216:217], off
	v_lshl_add_u64 v[218:219], s[42:43], 0, v[182:183]
	s_add_i32 m0, s69, 0x2000
	s_nop 0
	global_load_lds_dwordx4 v[218:219], off
	s_barrier
	s_waitcnt lgkmcnt(0)
	s_setprio 1
	s_waitcnt lgkmcnt(0)
	v_mfma_f32_16x16x32_bf16 v[116:119], v[192:195], v[144:147], v[116:119]
	v_mfma_f32_16x16x32_bf16 v[116:119], v[196:199], v[148:151], v[116:119]
	v_mfma_f32_16x16x32_bf16 v[100:103], v[196:199], v[156:159], v[100:103]
	v_mfma_f32_16x16x32_bf16 v[100:103], v[192:195], v[152:155], v[100:103]
	v_mfma_f32_16x16x32_bf16 v[84:87], v[192:195], v[160:163], v[84:87]
	v_mfma_f32_16x16x32_bf16 v[84:87], v[196:199], v[164:167], v[84:87]
	v_mfma_f32_16x16x32_bf16 v[68:71], v[196:199], v[172:175], v[68:71]
	v_mfma_f32_16x16x32_bf16 v[68:71], v[192:195], v[168:171], v[68:71]
	v_mfma_f32_16x16x32_bf16 v[64:67], v[200:203], v[168:171], v[64:67]
	v_mfma_f32_16x16x32_bf16 v[64:67], v[212:215], v[172:175], v[64:67]
	v_mfma_f32_16x16x32_bf16 v[80:83], v[212:215], v[164:167], v[80:83]
	v_mfma_f32_16x16x32_bf16 v[80:83], v[200:203], v[160:163], v[80:83]
	v_mfma_f32_16x16x32_bf16 v[96:99], v[200:203], v[152:155], v[96:99]
	v_mfma_f32_16x16x32_bf16 v[96:99], v[212:215], v[156:159], v[96:99]
	v_mfma_f32_16x16x32_bf16 v[112:115], v[212:215], v[148:151], v[112:115]
	v_mfma_f32_16x16x32_bf16 v[112:115], v[200:203], v[144:147], v[112:115]
	s_setprio 0
	s_mov_b32 m0, s54
	v_lshl_add_u64 v[220:221], s[44:45], 0, v[176:177]
	s_barrier
	ds_read_b128 v[144:147], v209 offset:16384
	ds_read_b128 v[148:151], v209 offset:17408
	ds_read_b128 v[152:155], v209 offset:18432
	ds_read_b128 v[156:159], v209 offset:19456
	ds_read_b128 v[160:163], v209 offset:20480
	ds_read_b128 v[164:167], v209 offset:21504
	ds_read_b128 v[168:171], v209 offset:22528
	ds_read_b128 v[172:175], v209 offset:23552
	global_load_lds_dwordx4 v[220:221], off
	v_lshl_add_u64 v[222:223], s[44:45], 0, v[180:181]
	s_mov_b32 m0, s55
	s_nop 0
	global_load_lds_dwordx4 v[222:223], off
	s_barrier
	s_waitcnt lgkmcnt(0)
	s_setprio 1
	s_waitcnt lgkmcnt(0)
	v_mfma_f32_16x16x32_bf16 v[60:63], v[128:131], v[144:147], v[60:63]
	v_mfma_f32_16x16x32_bf16 v[60:63], v[132:135], v[148:151], v[60:63]
	v_mfma_f32_16x16x32_bf16 v[44:47], v[132:135], v[156:159], v[44:47]
	v_mfma_f32_16x16x32_bf16 v[44:47], v[128:131], v[152:155], v[44:47]
	v_mfma_f32_16x16x32_bf16 v[28:31], v[128:131], v[160:163], v[28:31]
	v_mfma_f32_16x16x32_bf16 v[28:31], v[132:135], v[164:167], v[28:31]
	v_mfma_f32_16x16x32_bf16 v[12:15], v[132:135], v[172:175], v[12:15]
	v_mfma_f32_16x16x32_bf16 v[12:15], v[128:131], v[168:171], v[12:15]
	v_mfma_f32_16x16x32_bf16 v[8:11], v[136:139], v[168:171], v[8:11]
	v_mfma_f32_16x16x32_bf16 v[8:11], v[140:143], v[172:175], v[8:11]
	v_mfma_f32_16x16x32_bf16 v[24:27], v[140:143], v[164:167], v[24:27]
	v_mfma_f32_16x16x32_bf16 v[24:27], v[136:139], v[160:163], v[24:27]
	v_mfma_f32_16x16x32_bf16 v[40:43], v[136:139], v[152:155], v[40:43]
	v_mfma_f32_16x16x32_bf16 v[40:43], v[140:143], v[156:159], v[40:43]
	v_mfma_f32_16x16x32_bf16 v[56:59], v[140:143], v[148:151], v[56:59]
	v_mfma_f32_16x16x32_bf16 v[56:59], v[136:139], v[144:147], v[56:59]
	s_setprio 0
	s_barrier
; #define PG8_STAGE(bufoff, gbase, voff) do { _Pragma("unroll") for (int _i = 0; _i < 2; ++_i) \
;         __builtin_amdgcn_global_load_lds((const unsigned*)((const char*)(gbase) + (voff)[_i]), (LAS unsigned*)(lds + (bufoff) + ldsw + _i * 8192), 16, 0, 0); } while (0)
; #define PG8_LDA(dst, b, h) do { _Pragma("unroll") for (int m = 0; m < 4; ++m) _Pragma("unroll") for (int k = 0; k < 2; ++k) dst[m][k] = *(const LAS bf16x8*)(lds + PG8_SA(b, h) + aoff + m * 2048 + k * 1024); } while (0)
; #define PG8_LDB(dst, b, h) do { _Pragma("unroll") for (int n = 0; n < 2; ++n) _Pragma("unroll") for (int k = 0; k < 2; ++k) dst[n][k] = *(const LAS bf16x8*)(lds + PG8_SB(b, h) + boff + n * 2048 + k * 1024); } while (0)
; #define PG8_MMA(ai, bj, At, Bt) do { __builtin_amdgcn_s_setprio(1); _Pragma("unroll") for (int m = 0; m < 4; ++m) _Pragma("unroll") for (int n = 0; n < 2; ++n) _Pragma("unroll") for (int k = 0; k < 2; ++k) \
;         acc[ai][bj][m][n] = __builtin_amdgcn_mfma_f32_16x16x32_bf16(Bt[n][k], At[m][k], acc[ai][bj][m][n], 0, 0, 0); __builtin_amdgcn_s_setprio(0); } while (0)
; #define PG8_WAIT_V(n) asm volatile("s_waitcnt vmcnt(" #n ")" ::: "memory")
; #define PG8_WAIT_L(n) asm volatile("s_waitcnt lgkmcnt(" #n ")" ::: "memory")
; #define PG8_BAR __builtin_amdgcn_s_barrier()
; #define PG8_SCHED __builtin_amdgcn_sched_barrier(0)
; template <class Epi, class Ptrs>
; __device__ __forceinline__ void gemm_phase(LAS unsigned char* lds, const int K, const StaticOrder& S, const Ptrs& P, const Epi& E) {
;     ...
;             PG8_STAGE(PG8_SB(0, 1), b2 + hstep, voffB);
;             PG8_WAIT_V(6); PG8_BAR; PG8_MMA(1, 1, At, B1); PG8_BAR;
;             PG8_LDB(B0, 1, 0); PG8_SCHED; PG8_LDA(At, 1, 0); PG8_STAGE(PG8_SA(0, 1), a2 + hstep, voffA);
;             PG8_WAIT_L(8); PG8_BAR; PG8_WAIT_L(0); PG8_MMA(0, 0, At, B0); PG8_BAR; PG8_SCHED;
;             PG8_LDB(B1, 1, 1); PG8_STAGE(PG8_SB(1, 0), b3, voffB);
;             PG8_BAR; PG8_WAIT_L(0); PG8_MMA(0, 1, At, B1); PG8_BAR;
	s_add_u32 s70, s42, 0x40000
	s_addc_u32 s71, s43, 0
	s_add_i32 s69, s67, s51
	v_lshl_add_u64 v[128:129], s[70:71], 0, v[178:179]
	s_mov_b32 m0, s69
	s_nop 0
	global_load_lds_dwordx4 v[128:129], off
	v_lshl_add_u64 v[128:129], s[70:71], 0, v[182:183]
	s_add_i32 m0, s69, 0x2000
	s_nop 0
	global_load_lds_dwordx4 v[128:129], off
	s_waitcnt vmcnt(6)
	s_barrier
	s_setprio 1
	v_mfma_f32_16x16x32_bf16 v[52:55], v[192:195], v[144:147], v[52:55]
	v_mfma_f32_16x16x32_bf16 v[52:55], v[196:199], v[148:151], v[52:55]
	v_mfma_f32_16x16x32_bf16 v[36:39], v[196:199], v[156:159], v[36:39]
	v_mfma_f32_16x16x32_bf16 v[36:39], v[192:195], v[152:155], v[36:39]
	v_mfma_f32_16x16x32_bf16 v[20:23], v[192:195], v[160:163], v[20:23]
	v_mfma_f32_16x16x32_bf16 v[20:23], v[196:199], v[164:167], v[20:23]
	v_mfma_f32_16x16x32_bf16 v[4:7], v[196:199], v[172:175], v[4:7]
	v_mfma_f32_16x16x32_bf16 v[4:7], v[192:195], v[168:171], v[4:7]
	v_mfma_f32_16x16x32_bf16 v[0:3], v[200:203], v[168:171], v[0:3]
	v_mfma_f32_16x16x32_bf16 v[0:3], v[212:215], v[172:175], v[0:3]
	v_mfma_f32_16x16x32_bf16 v[16:19], v[212:215], v[164:167], v[16:19]
	v_mfma_f32_16x16x32_bf16 v[16:19], v[200:203], v[160:163], v[16:19]
	v_mfma_f32_16x16x32_bf16 v[32:35], v[200:203], v[152:155], v[32:35]
	v_mfma_f32_16x16x32_bf16 v[32:35], v[212:215], v[156:159], v[32:35]
	v_mfma_f32_16x16x32_bf16 v[48:51], v[212:215], v[148:151], v[48:51]
	v_mfma_f32_16x16x32_bf16 v[48:51], v[200:203], v[144:147], v[48:51]
	s_setprio 0
	s_add_i32 s69, 0, 0x18000
	v_add_u32_e32 v140, s69, v205
	s_barrier
	ds_read_b128 v[128:131], v140
	ds_read_b128 v[132:135], v140 offset:1024
	ds_read_b128 v[136:139], v140 offset:2048
	ds_read_b128 v[140:143], v140 offset:3072
	s_add_u32 s44, s44, 0x40000
	s_addc_u32 s45, s45, 0
	s_mov_b32 m0, s56
	v_lshl_add_u64 v[192:193], s[44:45], 0, v[176:177]
	ds_read_b128 v[144:147], v209 offset:32768
	ds_read_b128 v[148:151], v209 offset:33792
	ds_read_b128 v[152:155], v209 offset:34816
	ds_read_b128 v[156:159], v209 offset:35840
	ds_read_b128 v[160:163], v209 offset:36864
	ds_read_b128 v[164:167], v209 offset:37888
	ds_read_b128 v[168:171], v209 offset:38912
	ds_read_b128 v[172:175], v209 offset:39936
	global_load_lds_dwordx4 v[192:193], off
	v_lshl_add_u64 v[192:193], s[44:45], 0, v[180:181]
	s_mov_b32 m0, s57
	s_nop 0
	global_load_lds_dwordx4 v[192:193], off
	s_waitcnt lgkmcnt(8)
	s_barrier
	s_waitcnt lgkmcnt(0)
	s_setprio 1
	s_waitcnt lgkmcnt(0)
	v_mfma_f32_16x16x32_bf16 v[124:127], v[128:131], v[144:147], v[124:127]
	v_mfma_f32_16x16x32_bf16 v[124:127], v[132:135], v[148:151], v[124:127]
	v_mfma_f32_16x16x32_bf16 v[108:111], v[132:135], v[156:159], v[108:111]
	v_mfma_f32_16x16x32_bf16 v[108:111], v[128:131], v[152:155], v[108:111]
	v_mfma_f32_16x16x32_bf16 v[92:95], v[128:131], v[160:163], v[92:95]
	v_mfma_f32_16x16x32_bf16 v[92:95], v[132:135], v[164:167], v[92:95]
	v_mfma_f32_16x16x32_bf16 v[76:79], v[132:135], v[172:175], v[76:79]
	v_mfma_f32_16x16x32_bf16 v[76:79], v[128:131], v[168:171], v[76:79]
	v_mfma_f32_16x16x32_bf16 v[72:75], v[136:139], v[168:171], v[72:75]
	v_mfma_f32_16x16x32_bf16 v[72:75], v[140:143], v[172:175], v[72:75]
	v_mfma_f32_16x16x32_bf16 v[88:91], v[140:143], v[164:167], v[88:91]
	v_mfma_f32_16x16x32_bf16 v[88:91], v[136:139], v[160:163], v[88:91]
	v_mfma_f32_16x16x32_bf16 v[104:107], v[136:139], v[152:155], v[104:107]
	v_mfma_f32_16x16x32_bf16 v[104:107], v[140:143], v[156:159], v[104:107]
	v_mfma_f32_16x16x32_bf16 v[120:123], v[140:143], v[148:151], v[120:123]
	v_mfma_f32_16x16x32_bf16 v[120:123], v[136:139], v[144:147], v[120:123]
	s_setprio 0
	s_barrier
	s_add_i32 s44, 0, 0x1c000
	s_add_i32 s45, s69, s51
	v_add_u32_e32 v211, s44, v205
	v_lshl_add_u64 v[216:217], v[216:217], 0, s[18:19]
	s_mov_b32 m0, s45
	ds_read_b128 v[192:195], v211
	ds_read_b128 v[196:199], v211 offset:1024
	ds_read_b128 v[200:203], v211 offset:2048
	ds_read_b128 v[212:215], v211 offset:3072
	global_load_lds_dwordx4 v[216:217], off
	v_lshl_add_u64 v[216:217], v[218:219], 0, s[18:19]
	s_add_i32 m0, s45, 0x2000
	s_nop 0
	global_load_lds_dwordx4 v[216:217], off
	s_barrier
	s_waitcnt lgkmcnt(0)
	s_setprio 1
	s_waitcnt lgkmcnt(0)
	v_mfma_f32_16x16x32_bf16 v[116:119], v[192:195], v[144:147], v[116:119]
	v_mfma_f32_16x16x32_bf16 v[116:119], v[196:199], v[148:151], v[116:119]
	v_mfma_f32_16x16x32_bf16 v[100:103], v[196:199], v[156:159], v[100:103]
	v_mfma_f32_16x16x32_bf16 v[100:103], v[192:195], v[152:155], v[100:103]
	v_mfma_f32_16x16x32_bf16 v[84:87], v[192:195], v[160:163], v[84:87]
	v_mfma_f32_16x16x32_bf16 v[84:87], v[196:199], v[164:167], v[84:87]
	v_mfma_f32_16x16x32_bf16 v[68:71], v[196:199], v[172:175], v[68:71]
	v_mfma_f32_16x16x32_bf16 v[68:71], v[192:195], v[168:171], v[68:71]
	v_mfma_f32_16x16x32_bf16 v[64:67], v[200:203], v[168:171], v[64:67]
	v_mfma_f32_16x16x32_bf16 v[64:67], v[212:215], v[172:175], v[64:67]
	v_mfma_f32_16x16x32_bf16 v[80:83], v[212:215], v[164:167], v[80:83]
	v_mfma_f32_16x16x32_bf16 v[80:83], v[200:203], v[160:163], v[80:83]
	v_mfma_f32_16x16x32_bf16 v[96:99], v[200:203], v[152:155], v[96:99]
	v_mfma_f32_16x16x32_bf16 v[96:99], v[212:215], v[156:159], v[96:99]
	v_mfma_f32_16x16x32_bf16 v[112:115], v[212:215], v[148:151], v[112:115]
	v_mfma_f32_16x16x32_bf16 v[112:115], v[200:203], v[144:147], v[112:115]
	s_setprio 0
	s_mov_b32 m0, s63
	v_lshl_add_u64 v[216:217], v[220:221], 0, s[18:19]
	s_barrier
	ds_read_b128 v[144:147], v209 offset:49152
	ds_read_b128 v[148:151], v209 offset:50176
	ds_read_b128 v[152:155], v209 offset:51200
	ds_read_b128 v[156:159], v209 offset:52224
	ds_read_b128 v[160:163], v209 offset:53248
	ds_read_b128 v[164:167], v209 offset:54272
	ds_read_b128 v[168:171], v209 offset:55296
	ds_read_b128 v[172:175], v209 offset:56320
	global_load_lds_dwordx4 v[216:217], off
	v_lshl_add_u64 v[216:217], v[222:223], 0, s[18:19]
	s_mov_b32 m0, s64
	s_nop 0
	global_load_lds_dwordx4 v[216:217], off
	s_barrier
; __device__ __forceinline__ unsigned cvt_pk_bf16(float lo, float hi) { unsigned r; asm volatile("v_cvt_pk_bf16_f32 %0, %1, %2" : "=v"(r) : "v"(lo), "v"(hi)); return r; }
; __device__ __forceinline__ float x16_sum(float x) { auto s = __builtin_amdgcn_permlane16_swap(__float_as_uint(x), __float_as_uint(x), false, false); return __uint_as_float(s[0]) + __uint_as_float(s[1]); }
; template <class Epi, class Ptrs>
; __device__ __forceinline__ void gemm_phase(LAS unsigned char* lds, const int K, const StaticOrder& S, const Ptrs& P, const Epi& E) {
;     ...
;             PG8_LDA(At, 1, 1); PG8_STAGE(PG8_SA(1, 0), a3, voffA);
;             PG8_BAR; PG8_WAIT_L(0); PG8_MMA(1, 0, At, B0); PG8_BAR; PG8_SCHED;
;             PG8_STAGE(PG8_SB(1, 1), b3 + hstep, voffB);
;             PG8_WAIT_V(6); PG8_BAR; PG8_MMA(1, 1, At, B1); PG8_BAR;
;     __device__ __forceinline__ void operator()(const f32x4 (&acc)[2][2][4][2], const Unit& u, int ui, int wr, int wc, int fr, int fq) const {
;         const int row0 = u.pm * 256 + wr * 64 + fr, col0 = u.pn * 256 + wc * 32 + 8 * fq;
;         const float* xb0 = (u.pm * 256 < MP) ? xp : xs - (size_t)MP * DM;
; #pragma unroll
;         for (int ai = 0; ai < 2; ++ai) {
;             f32x4 xv[4][2][2];
; #pragma unroll
;             for (int m = 0; m < 4; ++m)
; #pragma unroll
;                 for (int bj = 0; bj < 2; ++bj) { const float* p = xb0 + (size_t)(row0 + ai * 128 + m * 16) * DM + col0 + bj * 128; xv[m][bj][0] = *(const f32x4*)p; xv[m][bj][1] = *(const f32x4*)(p + 4); }
; #pragma unroll
;             for (int m = 0; m < 4; ++m) { const int row = row0 + ai * 128 + m * 16; const size_t off = (size_t)row * DM + col0; float ss = 0.f;
; #pragma unroll
;                 for (int bj = 0; bj < 2; ++bj) {
;                     const f32x4 v0 = acc[ai][bj][m][0] + xv[m][bj][0], v1 = acc[ai][bj][m][1] + xv[m][bj][1];
;                     u32x4 w; w.x = cvt_pk_bf16(v0[0], v0[1]); w.y = cvt_pk_bf16(v0[2], v0[3]); w.z = cvt_pk_bf16(v1[0], v1[1]); w.w = cvt_pk_bf16(v1[2], v1[3]);
;                     *(u32x4*)(xb + off + bj * 128) = w;
;                     ss += (v0[0] * v0[0] + v0[1] * v0[1]) + (v0[2] * v0[2] + v0[3] * v0[3]) + (v1[0] * v1[0] + v1[1] * v1[1]) + (v1[2] * v1[2] + v1[3] * v1[3]); }
;                 ss = x32_sum(x16_sum(ss));
;                 if (fq == 0) part[(size_t)row * 16 + u.pn * 4 + wc] = ss; }
	s_waitcnt lgkmcnt(0)
	s_setprio 1
	s_waitcnt lgkmcnt(0)
	v_mfma_f32_16x16x32_bf16 v[60:63], v[128:131], v[144:147], v[60:63]
	v_mfma_f32_16x16x32_bf16 v[60:63], v[132:135], v[148:151], v[60:63]
	v_mfma_f32_16x16x32_bf16 v[44:47], v[132:135], v[156:159], v[44:47]
	v_mfma_f32_16x16x32_bf16 v[44:47], v[128:131], v[152:155], v[44:47]
	v_mfma_f32_16x16x32_bf16 v[28:31], v[128:131], v[160:163], v[28:31]
	v_mfma_f32_16x16x32_bf16 v[28:31], v[132:135], v[164:167], v[28:31]
	v_mfma_f32_16x16x32_bf16 v[12:15], v[132:135], v[172:175], v[12:15]
	v_mfma_f32_16x16x32_bf16 v[12:15], v[128:131], v[168:171], v[12:15]
	v_mfma_f32_16x16x32_bf16 v[8:11], v[136:139], v[168:171], v[8:11]
	v_mfma_f32_16x16x32_bf16 v[8:11], v[140:143], v[172:175], v[8:11]
	v_mfma_f32_16x16x32_bf16 v[24:27], v[140:143], v[164:167], v[24:27]
	v_mfma_f32_16x16x32_bf16 v[24:27], v[136:139], v[160:163], v[24:27]
	v_mfma_f32_16x16x32_bf16 v[40:43], v[136:139], v[152:155], v[40:43]
	v_mfma_f32_16x16x32_bf16 v[40:43], v[140:143], v[156:159], v[40:43]
	v_mfma_f32_16x16x32_bf16 v[56:59], v[140:143], v[148:151], v[56:59]
	v_mfma_f32_16x16x32_bf16 v[56:59], v[136:139], v[144:147], v[56:59]
	s_setprio 0
	s_barrier
	s_add_u32 s42, s42, 0x40080
	s_addc_u32 s43, s43, 0
	s_add_i32 s44, s44, s51
	v_lshl_add_u64 v[128:129], s[42:43], 0, v[178:179]
	s_mov_b32 m0, s44
	s_nop 0
	global_load_lds_dwordx4 v[128:129], off
	v_lshl_add_u64 v[128:129], s[42:43], 0, v[182:183]
	s_add_i32 m0, s44, 0x2000
	s_nop 0
	global_load_lds_dwordx4 v[128:129], off
	s_waitcnt vmcnt(6)
	s_barrier
	s_setprio 1
	v_mfma_f32_16x16x32_bf16 v[52:55], v[192:195], v[144:147], v[52:55]
	v_mfma_f32_16x16x32_bf16 v[52:55], v[196:199], v[148:151], v[52:55]
	v_mfma_f32_16x16x32_bf16 v[36:39], v[196:199], v[156:159], v[36:39]
	v_mfma_f32_16x16x32_bf16 v[36:39], v[192:195], v[152:155], v[36:39]
	v_mfma_f32_16x16x32_bf16 v[20:23], v[192:195], v[160:163], v[20:23]
	v_mfma_f32_16x16x32_bf16 v[20:23], v[196:199], v[164:167], v[20:23]
	v_mfma_f32_16x16x32_bf16 v[4:7], v[196:199], v[172:175], v[4:7]
	v_mfma_f32_16x16x32_bf16 v[4:7], v[192:195], v[168:171], v[4:7]
	v_mfma_f32_16x16x32_bf16 v[0:3], v[200:203], v[168:171], v[0:3]
	v_mfma_f32_16x16x32_bf16 v[0:3], v[212:215], v[172:175], v[0:3]
	v_mfma_f32_16x16x32_bf16 v[16:19], v[212:215], v[164:167], v[16:19]
	v_mfma_f32_16x16x32_bf16 v[16:19], v[200:203], v[160:163], v[16:19]
	v_mfma_f32_16x16x32_bf16 v[32:35], v[200:203], v[152:155], v[32:35]
	v_mfma_f32_16x16x32_bf16 v[32:35], v[212:215], v[156:159], v[32:35]
	v_mfma_f32_16x16x32_bf16 v[48:51], v[212:215], v[148:151], v[48:51]
	v_mfma_f32_16x16x32_bf16 v[48:51], v[200:203], v[144:147], v[48:51]
	s_setprio 0
	s_add_i32 s41, s41, 2
	s_add_u32 s38, s38, 0x100
	s_addc_u32 s39, s39, 0
	s_add_u32 s21, s21, 0x100
	s_addc_u32 s23, s23, 0
	s_cmp_gt_u32 s41, 13
	s_barrier
	s_cbranch_scc0 .LBB0_353
	s_cmpk_lt_i32 s40, 0x80
	v_lshl_add_u32 v194, s40, 8, v204
	v_lshl_or_b32 v192, s12, 8, v206
	s_cselect_b32 s21, s37, s61
	s_cselect_b32 s23, s36, s60
	v_mov_b32_e32 v128, s23
	v_mov_b32_e32 v129, s21
	v_ashrrev_i32_e32 v193, 31, v192
	v_ashrrev_i32_e32 v195, 31, v194
	v_lshl_add_u64 v[196:197], v[192:193], 2, v[128:129]
	v_lshlrev_b64 v[128:129], 12, v[194:195]
	v_or_b32_e32 v202, 16, v194
	v_or_b32_e32 v200, 32, v194
	v_or_b32_e32 v198, 48, v194
	v_lshl_add_u64 v[128:129], v[196:197], 0, v[128:129]
	v_ashrrev_i32_e32 v203, 31, v202
	v_ashrrev_i32_e32 v201, 31, v200
	v_ashrrev_i32_e32 v199, 31, v198
	global_load_dwordx4 v[212:215], v[128:129], off
	global_load_dwordx4 v[216:219], v[128:129], off offset:16
	global_load_dwordx4 v[220:223], v[128:129], off offset:512
	global_load_dwordx4 v[224:227], v[128:129], off offset:528
	v_lshlrev_b64 v[128:129], 12, v[202:203]
	v_lshlrev_b64 v[130:131], 12, v[200:201]
	v_lshlrev_b64 v[132:133], 12, v[198:199]
	v_lshl_add_u64 v[128:129], v[196:197], 0, v[128:129]
	v_lshl_add_u64 v[130:131], v[196:197], 0, v[130:131]
	v_lshl_add_u64 v[132:133], v[196:197], 0, v[132:133]
	global_load_dwordx4 v[168:171], v[128:129], off offset:16
	global_load_dwordx4 v[172:175], v[128:129], off
	global_load_dwordx4 v[160:163], v[128:129], off offset:528
	global_load_dwordx4 v[164:167], v[128:129], off offset:512
	global_load_dwordx4 v[152:155], v[130:131], off offset:16
	global_load_dwordx4 v[156:159], v[130:131], off
	global_load_dwordx4 v[144:147], v[130:131], off offset:528
	global_load_dwordx4 v[148:151], v[130:131], off offset:512
	global_load_dwordx4 v[136:139], v[132:133], off offset:16
	global_load_dwordx4 v[140:143], v[132:133], off
	s_nop 0
	global_load_dwordx4 v[128:131], v[132:133], off offset:528
	s_nop 0
	global_load_dwordx4 v[132:135], v[132:133], off offset:512
	v_lshlrev_b64 v[228:229], 11, v[194:195]
	v_lshl_add_u64 v[228:229], s[14:15], 0, v[228:229]
	v_lshl_add_u64 v[228:229], v[192:193], 1, v[228:229]
	s_lshl_b32 s38, s12, 2
	s_ashr_i32 s39, s38, 31
	s_waitcnt vmcnt(0)
	v_pk_add_f32 v[126:127], v[126:127], v[214:215]
	v_pk_add_f32 v[124:125], v[124:125], v[212:213]
	v_pk_add_f32 v[118:119], v[118:119], v[222:223]
	v_pk_add_f32 v[116:117], v[116:117], v[220:221]
	v_pk_add_f32 v[120:121], v[120:121], v[216:217]
	v_pk_add_f32 v[214:215], v[112:113], v[224:225]
	v_cvt_pk_bf16_f32 v112, v124, v125
	v_cvt_pk_bf16_f32 v113, v126, v127
	v_mul_f32_e32 v125, v125, v125
	v_mul_f32_e32 v127, v127, v127
	v_mul_f32_e32 v211, v117, v117
	v_mul_f32_e32 v216, v119, v119
	v_pk_add_f32 v[122:123], v[122:123], v[218:219]
	v_pk_add_f32 v[212:213], v[114:115], v[226:227]
	v_cvt_pk_bf16_f32 v114, v120, v121
	v_cvt_pk_bf16_f32 v115, v122, v123
	v_mul_f32_e32 v121, v121, v121
	v_mul_f32_e32 v217, v215, v215
	global_store_dwordx4 v[228:229], v[112:115], off
	v_fmac_f32_e32 v125, v124, v124
	v_fmac_f32_e32 v127, v126, v126
	v_cvt_pk_bf16_f32 v112, v116, v117
	v_fmac_f32_e32 v211, v116, v116
	v_fmac_f32_e32 v216, v118, v118
	v_mul_f32_e32 v123, v123, v123
	v_mul_f32_e32 v218, v213, v213
	v_fmac_f32_e32 v121, v120, v120
	v_cvt_pk_bf16_f32 v113, v118, v119
	v_cvt_pk_bf16_f32 v114, v214, v215
	v_cvt_pk_bf16_f32 v115, v212, v213
	v_fmac_f32_e32 v217, v214, v214
	v_add_f32_e32 v116, v125, v127
	global_store_dwordx4 v[228:229], v[112:115], off offset:256
	v_fmac_f32_e32 v123, v122, v122
	v_fmac_f32_e32 v218, v212, v212
	v_add_f32_e32 v112, v211, v216
	v_add_f32_e32 v113, v116, v121
	v_add_f32_e32 v112, v112, v217
	v_add_f32_e32 v113, v123, v113
	v_add_f32_e32 v112, v218, v112
	v_add_f32_e32 v112, v113, v112
	v_mov_b32_e32 v113, v112
	s_nop 1
	v_permlane16_swap_b32_e32 v112, v113
	v_add_f32_e32 v112, v112, v113
	v_mov_b32_e32 v113, v112
	s_nop 1
	v_permlane32_swap_b32_e32 v112, v113
	s_and_saveexec_b64 s[40:41], s[6:7]
	s_cbranch_execz .LBB0_356
	v_lshlrev_b64 v[114:115], 6, v[194:195]
	v_lshl_add_u64 v[114:115], s[16:17], 0, v[114:115]
	v_lshl_add_u64 v[114:115], s[38:39], 2, v[114:115]
	s_lshl_b32 s12, s62, 2
	v_lshl_add_u64 v[114:115], v[114:115], 0, s[12:13]
	v_add_f32_e32 v112, v112, v113
	global_store_dword v[114:115], v112, off

; #define PG8_STAGE(bufoff, gbase, voff) do { _Pragma("unroll") for (int _i = 0; _i < 2; ++_i) \
;         __builtin_amdgcn_global_load_lds((const unsigned*)((const char*)(gbase) + (voff)[_i]), (LAS unsigned*)(lds + (bufoff) + ldsw + _i * 8192), 16, 0, 0); } while (0)
; #define PG8_LDA(dst, b, h) do { _Pragma("unroll") for (int m = 0; m < 4; ++m) _Pragma("unroll") for (int k = 0; k < 2; ++k) dst[m][k] = *(const LAS bf16x8*)(lds + PG8_SA(b, h) + aoff + m * 2048 + k * 1024); } while (0)
; #define PG8_LDB(dst, b, h) do { _Pragma("unroll") for (int n = 0; n < 2; ++n) _Pragma("unroll") for (int k = 0; k < 2; ++k) dst[n][k] = *(const LAS bf16x8*)(lds + PG8_SB(b, h) + boff + n * 2048 + k * 1024); } while (0)
; #define PG8_MMA(ai, bj, At, Bt) do { __builtin_amdgcn_s_setprio(1); _Pragma("unroll") for (int m = 0; m < 4; ++m) _Pragma("unroll") for (int n = 0; n < 2; ++n) _Pragma("unroll") for (int k = 0; k < 2; ++k) \
;         acc[ai][bj][m][n] = __builtin_amdgcn_mfma_f32_16x16x32_bf16(Bt[n][k], At[m][k], acc[ai][bj][m][n], 0, 0, 0); __builtin_amdgcn_s_setprio(0); } while (0)
; #define PG8_WAIT_L(n) asm volatile("s_waitcnt lgkmcnt(" #n ")" ::: "memory")
; #define PG8_BAR __builtin_amdgcn_s_barrier()
; #define PG8_SCHED __builtin_amdgcn_sched_barrier(0)
; template <class Epi, class Ptrs>
; __device__ __forceinline__ void gemm_phase(LAS unsigned char* lds, const int K, const StaticOrder& S, const Ptrs& P, const Epi& E) {
;     ...
;         for (int t = 0; t < nt; t += 2) {
;             const bool last = (t == nt - 2);
;             const char* a1 = cA + (size_t)(t + 1) * kstep;
;             const char* a2 = last ? nA : cA + (size_t)(t + 2) * kstep; const char* b2 = last ? nB : cB + (size_t)(t + 2) * kstep;
;             const char* a3 = a2 + kstep; const char* b3 = b2 + kstep;
;             PG8_LDB(B0, 0, 0); PG8_SCHED; PG8_LDA(At, 0, 0); PG8_STAGE(PG8_SA(1, 1), a1 + hstep, voffA);
;             PG8_WAIT_L(8); PG8_BAR; PG8_WAIT_L(0); PG8_MMA(0, 0, At, B0); PG8_BAR; PG8_SCHED;
;             PG8_LDB(B1, 0, 1); PG8_STAGE(PG8_SB(0, 0), b2, voffB);
;             PG8_BAR; PG8_WAIT_L(0); PG8_MMA(0, 1, At, B1); PG8_BAR;
;             PG8_LDA(At, 0, 1); PG8_STAGE(PG8_SA(0, 0), a2, voffA);
;             PG8_BAR; PG8_WAIT_L(0); PG8_MMA(1, 0, At, B0); PG8_BAR; PG8_SCHED;
.LBB0_433:
	ds_read_b128 v[152:155], v149
	ds_read_b128 v[156:159], v149 offset:1024
	ds_read_b128 v[160:163], v149 offset:2048
	ds_read_b128 v[164:167], v149 offset:3072
	s_add_u32 s42, s40, 0xfffc0080
	s_addc_u32 s43, s41, -1
	s_cmp_eq_u32 s70, 12
	s_cselect_b32 s45, s1, s43
	s_cselect_b32 s44, s0, s42
	s_cselect_b32 s43, s37, s25
	s_cselect_b32 s42, s36, s23
	v_lshl_add_u64 v[144:145], s[40:41], 0, v[136:137]
	s_add_i32 m0, s39, 0xc000
	ds_read_b128 v[168:171], v150
	ds_read_b128 v[172:175], v150 offset:1024
	ds_read_b128 v[176:179], v150 offset:2048
	ds_read_b128 v[180:183], v150 offset:3072
	ds_read_b128 v[184:187], v150 offset:4096
	ds_read_b128 v[188:191], v150 offset:5120
	ds_read_b128 v[192:195], v150 offset:6144
	ds_read_b128 v[196:199], v150 offset:7168
	global_load_lds_dwordx4 v[144:145], off
	v_lshl_add_u64 v[144:145], s[40:41], 0, v[138:139]
	s_add_i32 m0, s39, 0xe000
	s_nop 0
	global_load_lds_dwordx4 v[144:145], off
	s_waitcnt lgkmcnt(8)
	s_barrier
	s_waitcnt lgkmcnt(0)
	s_setprio 1
	s_waitcnt lgkmcnt(0)
	v_mfma_f32_16x16x32_bf16 v[124:127], v[152:155], v[168:171], v[124:127]
	v_mfma_f32_16x16x32_bf16 v[124:127], v[156:159], v[172:175], v[124:127]
	v_mfma_f32_16x16x32_bf16 v[108:111], v[156:159], v[180:183], v[108:111]
	v_mfma_f32_16x16x32_bf16 v[108:111], v[152:155], v[176:179], v[108:111]
	v_mfma_f32_16x16x32_bf16 v[92:95], v[152:155], v[184:187], v[92:95]
	v_mfma_f32_16x16x32_bf16 v[92:95], v[156:159], v[188:191], v[92:95]
	v_mfma_f32_16x16x32_bf16 v[76:79], v[156:159], v[196:199], v[76:79]
	v_mfma_f32_16x16x32_bf16 v[76:79], v[152:155], v[192:195], v[76:79]
	v_mfma_f32_16x16x32_bf16 v[72:75], v[160:163], v[192:195], v[72:75]
	v_mfma_f32_16x16x32_bf16 v[72:75], v[164:167], v[196:199], v[72:75]
	v_mfma_f32_16x16x32_bf16 v[88:91], v[164:167], v[188:191], v[88:91]
	v_mfma_f32_16x16x32_bf16 v[88:91], v[160:163], v[184:187], v[88:91]
	v_mfma_f32_16x16x32_bf16 v[104:107], v[160:163], v[176:179], v[104:107]
	v_mfma_f32_16x16x32_bf16 v[104:107], v[164:167], v[180:183], v[104:107]
	v_mfma_f32_16x16x32_bf16 v[120:123], v[164:167], v[172:175], v[120:123]
	v_mfma_f32_16x16x32_bf16 v[120:123], v[160:163], v[168:171], v[120:123]
	s_setprio 0
	s_barrier
	s_add_i32 s71, s63, s51
	v_lshl_add_u64 v[144:145], s[42:43], 0, v[130:131]
	s_mov_b32 m0, s71
	ds_read_b128 v[200:203], v151
	ds_read_b128 v[204:207], v151 offset:1024
	ds_read_b128 v[210:213], v151 offset:2048
	ds_read_b128 v[214:217], v151 offset:3072
	global_load_lds_dwordx4 v[144:145], off
	v_lshl_add_u64 v[218:219], s[42:43], 0, v[134:135]
	s_add_i32 m0, s71, 0x2000
	s_nop 0
	global_load_lds_dwordx4 v[218:219], off
	s_barrier
	s_waitcnt lgkmcnt(0)
	s_setprio 1
	s_waitcnt lgkmcnt(0)
	v_mfma_f32_16x16x32_bf16 v[116:119], v[200:203], v[168:171], v[116:119]
	v_mfma_f32_16x16x32_bf16 v[116:119], v[204:207], v[172:175], v[116:119]
	v_mfma_f32_16x16x32_bf16 v[100:103], v[204:207], v[180:183], v[100:103]
	v_mfma_f32_16x16x32_bf16 v[100:103], v[200:203], v[176:179], v[100:103]
	v_mfma_f32_16x16x32_bf16 v[84:87], v[200:203], v[184:187], v[84:87]
	v_mfma_f32_16x16x32_bf16 v[84:87], v[204:207], v[188:191], v[84:87]
	v_mfma_f32_16x16x32_bf16 v[68:71], v[204:207], v[196:199], v[68:71]
	v_mfma_f32_16x16x32_bf16 v[68:71], v[200:203], v[192:195], v[68:71]
	v_mfma_f32_16x16x32_bf16 v[64:67], v[210:213], v[192:195], v[64:67]
	v_mfma_f32_16x16x32_bf16 v[64:67], v[214:217], v[196:199], v[64:67]
	v_mfma_f32_16x16x32_bf16 v[80:83], v[214:217], v[188:191], v[80:83]
	v_mfma_f32_16x16x32_bf16 v[80:83], v[210:213], v[184:187], v[80:83]
	v_mfma_f32_16x16x32_bf16 v[96:99], v[210:213], v[176:179], v[96:99]
	v_mfma_f32_16x16x32_bf16 v[96:99], v[214:217], v[180:183], v[96:99]
	v_mfma_f32_16x16x32_bf16 v[112:115], v[214:217], v[172:175], v[112:115]
	v_mfma_f32_16x16x32_bf16 v[112:115], v[210:213], v[168:171], v[112:115]
	s_setprio 0
	s_mov_b32 m0, s39
	v_lshl_add_u64 v[220:221], s[44:45], 0, v[128:129]
	s_barrier
	ds_read_b128 v[168:171], v150 offset:16384
	ds_read_b128 v[172:175], v150 offset:17408
	ds_read_b128 v[176:179], v150 offset:18432
	ds_read_b128 v[180:183], v150 offset:19456
	ds_read_b128 v[184:187], v150 offset:20480
	ds_read_b128 v[188:191], v150 offset:21504
	ds_read_b128 v[192:195], v150 offset:22528
	ds_read_b128 v[196:199], v150 offset:23552
	global_load_lds_dwordx4 v[220:221], off
	v_lshl_add_u64 v[222:223], s[44:45], 0, v[132:133]
	s_mov_b32 m0, s56
	s_nop 0
	global_load_lds_dwordx4 v[222:223], off
	s_barrier
	s_waitcnt lgkmcnt(0)
	s_setprio 1
	s_waitcnt lgkmcnt(0)
	v_mfma_f32_16x16x32_bf16 v[60:63], v[152:155], v[168:171], v[60:63]
	v_mfma_f32_16x16x32_bf16 v[60:63], v[156:159], v[172:175], v[60:63]
	v_mfma_f32_16x16x32_bf16 v[44:47], v[156:159], v[180:183], v[44:47]
	v_mfma_f32_16x16x32_bf16 v[44:47], v[152:155], v[176:179], v[44:47]
	v_mfma_f32_16x16x32_bf16 v[28:31], v[152:155], v[184:187], v[28:31]
	v_mfma_f32_16x16x32_bf16 v[28:31], v[156:159], v[188:191], v[28:31]
	v_mfma_f32_16x16x32_bf16 v[12:15], v[156:159], v[196:199], v[12:15]
	v_mfma_f32_16x16x32_bf16 v[12:15], v[152:155], v[192:195], v[12:15]
	v_mfma_f32_16x16x32_bf16 v[8:11], v[160:163], v[192:195], v[8:11]
	v_mfma_f32_16x16x32_bf16 v[8:11], v[164:167], v[196:199], v[8:11]
	v_mfma_f32_16x16x32_bf16 v[24:27], v[164:167], v[188:191], v[24:27]
	v_mfma_f32_16x16x32_bf16 v[24:27], v[160:163], v[184:187], v[24:27]
	v_mfma_f32_16x16x32_bf16 v[40:43], v[160:163], v[176:179], v[40:43]
	v_mfma_f32_16x16x32_bf16 v[40:43], v[164:167], v[180:183], v[40:43]
	v_mfma_f32_16x16x32_bf16 v[56:59], v[164:167], v[172:175], v[56:59]
	v_mfma_f32_16x16x32_bf16 v[56:59], v[160:163], v[168:171], v[56:59]
	s_setprio 0
	s_barrier
; #define PG8_STAGE(bufoff, gbase, voff) do { _Pragma("unroll") for (int _i = 0; _i < 2; ++_i) \
;         __builtin_amdgcn_global_load_lds((const unsigned*)((const char*)(gbase) + (voff)[_i]), (LAS unsigned*)(lds + (bufoff) + ldsw + _i * 8192), 16, 0, 0); } while (0)
; #define PG8_LDA(dst, b, h) do { _Pragma("unroll") for (int m = 0; m < 4; ++m) _Pragma("unroll") for (int k = 0; k < 2; ++k) dst[m][k] = *(const LAS bf16x8*)(lds + PG8_SA(b, h) + aoff + m * 2048 + k * 1024); } while (0)
; #define PG8_LDB(dst, b, h) do { _Pragma("unroll") for (int n = 0; n < 2; ++n) _Pragma("unroll") for (int k = 0; k < 2; ++k) dst[n][k] = *(const LAS bf16x8*)(lds + PG8_SB(b, h) + boff + n * 2048 + k * 1024); } while (0)
; #define PG8_MMA(ai, bj, At, Bt) do { __builtin_amdgcn_s_setprio(1); _Pragma("unroll") for (int m = 0; m < 4; ++m) _Pragma("unroll") for (int n = 0; n < 2; ++n) _Pragma("unroll") for (int k = 0; k < 2; ++k) \
;         acc[ai][bj][m][n] = __builtin_amdgcn_mfma_f32_16x16x32_bf16(Bt[n][k], At[m][k], acc[ai][bj][m][n], 0, 0, 0); __builtin_amdgcn_s_setprio(0); } while (0)
; #define PG8_WAIT_V(n) asm volatile("s_waitcnt vmcnt(" #n ")" ::: "memory")
; #define PG8_WAIT_L(n) asm volatile("s_waitcnt lgkmcnt(" #n ")" ::: "memory")
; #define PG8_BAR __builtin_amdgcn_s_barrier()
; #define PG8_SCHED __builtin_amdgcn_sched_barrier(0)
; template <class Epi, class Ptrs>
; __device__ __forceinline__ void gemm_phase(LAS unsigned char* lds, const int K, const StaticOrder& S, const Ptrs& P, const Epi& E) {
;     ...
;             PG8_STAGE(PG8_SB(0, 1), b2 + hstep, voffB);
;             PG8_WAIT_V(6); PG8_BAR; PG8_MMA(1, 1, At, B1); PG8_BAR;
;             PG8_LDB(B0, 1, 0); PG8_SCHED; PG8_LDA(At, 1, 0); PG8_STAGE(PG8_SA(0, 1), a2 + hstep, voffA);
;             PG8_WAIT_L(8); PG8_BAR; PG8_WAIT_L(0); PG8_MMA(0, 0, At, B0); PG8_BAR; PG8_SCHED;
;             PG8_LDB(B1, 1, 1); PG8_STAGE(PG8_SB(1, 0), b3, voffB);
;             PG8_BAR; PG8_WAIT_L(0); PG8_MMA(0, 1, At, B1); PG8_BAR;
	s_add_u32 s72, s42, 0x40000
	s_addc_u32 s73, s43, 0
	s_add_i32 s71, s64, s51
	v_lshl_add_u64 v[152:153], s[72:73], 0, v[130:131]
	s_mov_b32 m0, s71
	s_nop 0
	global_load_lds_dwordx4 v[152:153], off
	v_lshl_add_u64 v[152:153], s[72:73], 0, v[134:135]
	s_add_i32 m0, s71, 0x2000
	s_nop 0
	global_load_lds_dwordx4 v[152:153], off
	s_waitcnt vmcnt(6)
	s_barrier
	s_setprio 1
	v_mfma_f32_16x16x32_bf16 v[52:55], v[200:203], v[168:171], v[52:55]
	v_mfma_f32_16x16x32_bf16 v[52:55], v[204:207], v[172:175], v[52:55]
	v_mfma_f32_16x16x32_bf16 v[36:39], v[204:207], v[180:183], v[36:39]
	v_mfma_f32_16x16x32_bf16 v[36:39], v[200:203], v[176:179], v[36:39]
	v_mfma_f32_16x16x32_bf16 v[20:23], v[200:203], v[184:187], v[20:23]
	v_mfma_f32_16x16x32_bf16 v[20:23], v[204:207], v[188:191], v[20:23]
	v_mfma_f32_16x16x32_bf16 v[4:7], v[204:207], v[196:199], v[4:7]
	v_mfma_f32_16x16x32_bf16 v[4:7], v[200:203], v[192:195], v[4:7]
	v_mfma_f32_16x16x32_bf16 v[0:3], v[210:213], v[192:195], v[0:3]
	v_mfma_f32_16x16x32_bf16 v[0:3], v[214:217], v[196:199], v[0:3]
	v_mfma_f32_16x16x32_bf16 v[16:19], v[214:217], v[188:191], v[16:19]
	v_mfma_f32_16x16x32_bf16 v[16:19], v[210:213], v[184:187], v[16:19]
	v_mfma_f32_16x16x32_bf16 v[32:35], v[210:213], v[176:179], v[32:35]
	v_mfma_f32_16x16x32_bf16 v[32:35], v[214:217], v[180:183], v[32:35]
	v_mfma_f32_16x16x32_bf16 v[48:51], v[214:217], v[172:175], v[48:51]
	v_mfma_f32_16x16x32_bf16 v[48:51], v[210:213], v[168:171], v[48:51]
	s_setprio 0
	s_add_i32 s71, 0, 0x18000
	v_add_u32_e32 v164, s71, v147
	s_barrier
	ds_read_b128 v[152:155], v164
	ds_read_b128 v[156:159], v164 offset:1024
	ds_read_b128 v[160:163], v164 offset:2048
	ds_read_b128 v[164:167], v164 offset:3072
	s_add_u32 s44, s44, 0x40000
	s_addc_u32 s45, s45, 0
	s_mov_b32 m0, s57
	v_lshl_add_u64 v[200:201], s[44:45], 0, v[128:129]
	ds_read_b128 v[168:171], v150 offset:32768
	ds_read_b128 v[172:175], v150 offset:33792
	ds_read_b128 v[176:179], v150 offset:34816
	ds_read_b128 v[180:183], v150 offset:35840
	ds_read_b128 v[184:187], v150 offset:36864
	ds_read_b128 v[188:191], v150 offset:37888
	ds_read_b128 v[192:195], v150 offset:38912
	ds_read_b128 v[196:199], v150 offset:39936
	global_load_lds_dwordx4 v[200:201], off
	v_lshl_add_u64 v[200:201], s[44:45], 0, v[132:133]
	s_mov_b32 m0, s58
	s_nop 0
	global_load_lds_dwordx4 v[200:201], off
	s_waitcnt lgkmcnt(8)
	s_barrier
	s_waitcnt lgkmcnt(0)
	s_setprio 1
	s_waitcnt lgkmcnt(0)
	v_mfma_f32_16x16x32_bf16 v[124:127], v[152:155], v[168:171], v[124:127]
	v_mfma_f32_16x16x32_bf16 v[124:127], v[156:159], v[172:175], v[124:127]
	v_mfma_f32_16x16x32_bf16 v[108:111], v[156:159], v[180:183], v[108:111]
	v_mfma_f32_16x16x32_bf16 v[108:111], v[152:155], v[176:179], v[108:111]
	v_mfma_f32_16x16x32_bf16 v[92:95], v[152:155], v[184:187], v[92:95]
	v_mfma_f32_16x16x32_bf16 v[92:95], v[156:159], v[188:191], v[92:95]
	v_mfma_f32_16x16x32_bf16 v[76:79], v[156:159], v[196:199], v[76:79]
	v_mfma_f32_16x16x32_bf16 v[76:79], v[152:155], v[192:195], v[76:79]
	v_mfma_f32_16x16x32_bf16 v[72:75], v[160:163], v[192:195], v[72:75]
	v_mfma_f32_16x16x32_bf16 v[72:75], v[164:167], v[196:199], v[72:75]
	v_mfma_f32_16x16x32_bf16 v[88:91], v[164:167], v[188:191], v[88:91]
	v_mfma_f32_16x16x32_bf16 v[88:91], v[160:163], v[184:187], v[88:91]
	v_mfma_f32_16x16x32_bf16 v[104:107], v[160:163], v[176:179], v[104:107]
	v_mfma_f32_16x16x32_bf16 v[104:107], v[164:167], v[180:183], v[104:107]
	v_mfma_f32_16x16x32_bf16 v[120:123], v[164:167], v[172:175], v[120:123]
	v_mfma_f32_16x16x32_bf16 v[120:123], v[160:163], v[168:171], v[120:123]
	s_setprio 0
	s_barrier
	s_add_i32 s44, 0, 0x1c000
	s_add_i32 s45, s71, s51
	v_add_u32_e32 v209, s44, v147
	v_lshl_add_u64 v[144:145], v[144:145], 0, s[12:13]
	s_mov_b32 m0, s45
	ds_read_b128 v[200:203], v209
	ds_read_b128 v[204:207], v209 offset:1024
	ds_read_b128 v[210:213], v209 offset:2048
	ds_read_b128 v[214:217], v209 offset:3072
	global_load_lds_dwordx4 v[144:145], off
	v_lshl_add_u64 v[144:145], v[218:219], 0, s[12:13]
	s_add_i32 m0, s45, 0x2000
	s_nop 0
	global_load_lds_dwordx4 v[144:145], off
	s_barrier
	s_waitcnt lgkmcnt(0)
	s_setprio 1
	s_waitcnt lgkmcnt(0)
	v_mfma_f32_16x16x32_bf16 v[116:119], v[200:203], v[168:171], v[116:119]
	v_mfma_f32_16x16x32_bf16 v[116:119], v[204:207], v[172:175], v[116:119]
	v_mfma_f32_16x16x32_bf16 v[100:103], v[204:207], v[180:183], v[100:103]
	v_mfma_f32_16x16x32_bf16 v[100:103], v[200:203], v[176:179], v[100:103]
	v_mfma_f32_16x16x32_bf16 v[84:87], v[200:203], v[184:187], v[84:87]
	v_mfma_f32_16x16x32_bf16 v[84:87], v[204:207], v[188:191], v[84:87]
	v_mfma_f32_16x16x32_bf16 v[68:71], v[204:207], v[196:199], v[68:71]
	v_mfma_f32_16x16x32_bf16 v[68:71], v[200:203], v[192:195], v[68:71]
	v_mfma_f32_16x16x32_bf16 v[64:67], v[210:213], v[192:195], v[64:67]
	v_mfma_f32_16x16x32_bf16 v[64:67], v[214:217], v[196:199], v[64:67]
	v_mfma_f32_16x16x32_bf16 v[80:83], v[214:217], v[188:191], v[80:83]
	v_mfma_f32_16x16x32_bf16 v[80:83], v[210:213], v[184:187], v[80:83]
	v_mfma_f32_16x16x32_bf16 v[96:99], v[210:213], v[176:179], v[96:99]
	v_mfma_f32_16x16x32_bf16 v[96:99], v[214:217], v[180:183], v[96:99]
	v_mfma_f32_16x16x32_bf16 v[112:115], v[214:217], v[172:175], v[112:115]
	v_mfma_f32_16x16x32_bf16 v[112:115], v[210:213], v[168:171], v[112:115]
	s_setprio 0
	s_mov_b32 m0, s61
	v_lshl_add_u64 v[144:145], v[220:221], 0, s[12:13]
	s_barrier
	ds_read_b128 v[168:171], v150 offset:49152
	ds_read_b128 v[172:175], v150 offset:50176
	ds_read_b128 v[176:179], v150 offset:51200
	ds_read_b128 v[180:183], v150 offset:52224
	ds_read_b128 v[184:187], v150 offset:53248
	ds_read_b128 v[188:191], v150 offset:54272
	ds_read_b128 v[192:195], v150 offset:55296
	ds_read_b128 v[196:199], v150 offset:56320
	global_load_lds_dwordx4 v[144:145], off
	v_lshl_add_u64 v[144:145], v[222:223], 0, s[12:13]
	s_mov_b32 m0, s62
	s_nop 0
	global_load_lds_dwordx4 v[144:145], off
	s_barrier
; __device__ __forceinline__ unsigned cvt_pk_bf16(float lo, float hi) { unsigned r; asm volatile("v_cvt_pk_bf16_f32 %0, %1, %2" : "=v"(r) : "v"(lo), "v"(hi)); return r; }
; #define PG8_STAGE(bufoff, gbase, voff) do { _Pragma("unroll") for (int _i = 0; _i < 2; ++_i) \
;         __builtin_amdgcn_global_load_lds((const unsigned*)((const char*)(gbase) + (voff)[_i]), (LAS unsigned*)(lds + (bufoff) + ldsw + _i * 8192), 16, 0, 0); } while (0)
; #define PG8_LDA(dst, b, h) do { _Pragma("unroll") for (int m = 0; m < 4; ++m) _Pragma("unroll") for (int k = 0; k < 2; ++k) dst[m][k] = *(const LAS bf16x8*)(lds + PG8_SA(b, h) + aoff + m * 2048 + k * 1024); } while (0)
; #define PG8_MMA(ai, bj, At, Bt) do { __builtin_amdgcn_s_setprio(1); _Pragma("unroll") for (int m = 0; m < 4; ++m) _Pragma("unroll") for (int n = 0; n < 2; ++n) _Pragma("unroll") for (int k = 0; k < 2; ++k) \
;         acc[ai][bj][m][n] = __builtin_amdgcn_mfma_f32_16x16x32_bf16(Bt[n][k], At[m][k], acc[ai][bj][m][n], 0, 0, 0); __builtin_amdgcn_s_setprio(0); } while (0)
; #define PG8_WAIT_V(n) asm volatile("s_waitcnt vmcnt(" #n ")" ::: "memory")
; template <class Epi, class Ptrs>
; __device__ __forceinline__ void gemm_phase(LAS unsigned char* lds, const int K, const StaticOrder& S, const Ptrs& P, const Epi& E) {
;     ...
;             PG8_LDA(At, 1, 1); PG8_STAGE(PG8_SA(1, 0), a3, voffA);
;             PG8_BAR; PG8_WAIT_L(0); PG8_MMA(1, 0, At, B0); PG8_BAR; PG8_SCHED;
;             PG8_STAGE(PG8_SB(1, 1), b3 + hstep, voffB);
;             PG8_WAIT_V(6); PG8_BAR; PG8_MMA(1, 1, At, B1); PG8_BAR;
;     __device__ __forceinline__ void operator()(const f32x4 (&acc)[2][2][4][2], const Unit& u, int ui, int wr, int wc, int fr, int fq) const {
;     ...
; #pragma unroll
;         for (int ai = 0; ai < 2; ++ai)
; #pragma unroll
;             for (int m = 0; m < 4; ++m) { bf16_t* rowp = hid + (size_t)(row0 + ai * 128 + m * 16) * DFF + col0;
; #pragma unroll
;                 for (int bj = 0; bj < 2; ++bj) { f32x4 v0 = acc[ai][bj][m][0], v1 = acc[ai][bj][m][1];
; #pragma unroll
;                     for (int j = 0; j < 4; ++j) { const float a = fmaxf(v0[j], 0.f), b = fmaxf(v1[j], 0.f); v0[j] = a * a; v1[j] = b * b; }
;                     u32x4 w; w.x = cvt_pk_bf16(v0[0], v0[1]); w.y = cvt_pk_bf16(v0[2], v0[3]); w.z = cvt_pk_bf16(v1[0], v1[1]); w.w = cvt_pk_bf16(v1[2], v1[3]);
;                     *(u32x4*)(rowp + bj * 128) = w; } }
	s_waitcnt lgkmcnt(0)
	s_setprio 1
	s_waitcnt lgkmcnt(0)
	v_mfma_f32_16x16x32_bf16 v[60:63], v[152:155], v[168:171], v[60:63]
	v_mfma_f32_16x16x32_bf16 v[60:63], v[156:159], v[172:175], v[60:63]
	v_mfma_f32_16x16x32_bf16 v[44:47], v[156:159], v[180:183], v[44:47]
	v_mfma_f32_16x16x32_bf16 v[44:47], v[152:155], v[176:179], v[44:47]
	v_mfma_f32_16x16x32_bf16 v[28:31], v[152:155], v[184:187], v[28:31]
	v_mfma_f32_16x16x32_bf16 v[28:31], v[156:159], v[188:191], v[28:31]
	v_mfma_f32_16x16x32_bf16 v[12:15], v[156:159], v[196:199], v[12:15]
	v_mfma_f32_16x16x32_bf16 v[12:15], v[152:155], v[192:195], v[12:15]
	v_mfma_f32_16x16x32_bf16 v[8:11], v[160:163], v[192:195], v[8:11]
	v_mfma_f32_16x16x32_bf16 v[8:11], v[164:167], v[196:199], v[8:11]
	v_mfma_f32_16x16x32_bf16 v[24:27], v[164:167], v[188:191], v[24:27]
	v_mfma_f32_16x16x32_bf16 v[24:27], v[160:163], v[184:187], v[24:27]
	v_mfma_f32_16x16x32_bf16 v[40:43], v[160:163], v[176:179], v[40:43]
	v_mfma_f32_16x16x32_bf16 v[40:43], v[164:167], v[180:183], v[40:43]
	v_mfma_f32_16x16x32_bf16 v[56:59], v[164:167], v[172:175], v[56:59]
	v_mfma_f32_16x16x32_bf16 v[56:59], v[160:163], v[168:171], v[56:59]
	s_setprio 0
	s_barrier
	s_add_u32 s42, s42, 0x40080
	s_addc_u32 s43, s43, 0
	s_add_i32 s44, s44, s51
	v_lshl_add_u64 v[144:145], s[42:43], 0, v[130:131]
	s_mov_b32 m0, s44
	s_nop 0
	global_load_lds_dwordx4 v[144:145], off
	v_lshl_add_u64 v[144:145], s[42:43], 0, v[134:135]
	s_add_i32 m0, s44, 0x2000
	s_nop 0
	global_load_lds_dwordx4 v[144:145], off
	s_waitcnt vmcnt(6)
	s_barrier
	s_setprio 1
	v_mfma_f32_16x16x32_bf16 v[52:55], v[200:203], v[168:171], v[52:55]
	v_mfma_f32_16x16x32_bf16 v[52:55], v[204:207], v[172:175], v[52:55]
	v_mfma_f32_16x16x32_bf16 v[36:39], v[204:207], v[180:183], v[36:39]
	v_mfma_f32_16x16x32_bf16 v[36:39], v[200:203], v[176:179], v[36:39]
	v_mfma_f32_16x16x32_bf16 v[20:23], v[200:203], v[184:187], v[20:23]
	v_mfma_f32_16x16x32_bf16 v[20:23], v[204:207], v[188:191], v[20:23]
	v_mfma_f32_16x16x32_bf16 v[4:7], v[204:207], v[196:199], v[4:7]
	v_mfma_f32_16x16x32_bf16 v[4:7], v[200:203], v[192:195], v[4:7]
	v_mfma_f32_16x16x32_bf16 v[0:3], v[210:213], v[192:195], v[0:3]
	v_mfma_f32_16x16x32_bf16 v[0:3], v[214:217], v[196:199], v[0:3]
	v_mfma_f32_16x16x32_bf16 v[16:19], v[214:217], v[188:191], v[16:19]
	v_mfma_f32_16x16x32_bf16 v[16:19], v[210:213], v[184:187], v[16:19]
	v_mfma_f32_16x16x32_bf16 v[32:35], v[210:213], v[176:179], v[32:35]
	v_mfma_f32_16x16x32_bf16 v[32:35], v[214:217], v[180:183], v[32:35]
	v_mfma_f32_16x16x32_bf16 v[48:51], v[214:217], v[172:175], v[48:51]
	v_mfma_f32_16x16x32_bf16 v[48:51], v[210:213], v[168:171], v[48:51]
	s_setprio 0
	s_add_i32 s70, s70, 2
	s_add_u32 s40, s40, 0x100
	s_addc_u32 s41, s41, 0
	s_add_u32 s23, s23, 0x100
	s_addc_u32 s25, s25, 0
	s_cmp_gt_u32 s70, 13
	s_barrier
	s_cbranch_scc0 .LBB0_433
	v_lshl_add_u32 v152, s38, 8, v146
	v_max_f32_e32 v120, v120, v120
	v_ashrrev_i32_e32 v153, 31, v152
	v_max_f32_e32 v120, 0, v120
	v_max_f32_e32 v121, v121, v121
	v_max_f32_e32 v122, v122, v122
	v_lshl_or_b32 v144, s69, 8, v148
	v_lshlrev_b64 v[154:155], 13, v[152:153]
	v_mul_f32_e32 v153, v120, v120
	v_max_f32_e32 v120, v125, v125
	v_max_f32_e32 v121, 0, v121
	v_max_f32_e32 v122, 0, v122
	v_ashrrev_i32_e32 v145, 31, v144
	v_max_f32_e32 v124, v124, v124
	v_max_f32_e32 v120, 0, v120
	v_mul_f32_e32 v125, v121, v121
	v_max_f32_e32 v121, v126, v126
	v_mul_f32_e32 v126, v122, v122
	v_max_f32_e32 v122, v127, v127
	v_max_f32_e32 v123, v123, v123
	v_lshl_add_u64 v[154:155], s[10:11], 0, v[154:155]
	v_lshlrev_b64 v[156:157], 1, v[144:145]
	v_max_f32_e32 v124, 0, v124
	v_mul_f32_e32 v120, v120, v120
	v_max_f32_e32 v121, 0, v121
	v_max_f32_e32 v122, 0, v122
	v_max_f32_e32 v123, 0, v123
	v_max_f32_e32 v112, v112, v112
	v_lshl_add_u64 v[144:145], v[154:155], 0, v[156:157]
	v_mul_f32_e32 v124, v124, v124
	v_mul_f32_e32 v121, v121, v121
	v_mul_f32_e32 v122, v122, v122
	v_mul_f32_e32 v123, v123, v123
	v_cvt_pk_bf16_f32 v120, v124, v120
	v_max_f32_e32 v112, 0, v112
	v_max_f32_e32 v113, v113, v113
	v_max_f32_e32 v114, v114, v114
	v_cvt_pk_bf16_f32 v121, v121, v122
	v_cvt_pk_bf16_f32 v122, v153, v125
	v_cvt_pk_bf16_f32 v123, v126, v123
	global_store_dwordx4 v[144:145], v[120:123], off
	v_max_f32_e32 v113, 0, v113
	v_max_f32_e32 v114, 0, v114
	v_mul_f32_e32 v120, v112, v112
	v_max_f32_e32 v112, v117, v117
	v_max_f32_e32 v116, v116, v116
	v_max_f32_e32 v112, 0, v112
	v_mul_f32_e32 v117, v113, v113
	v_max_f32_e32 v113, v118, v118
	v_mul_f32_e32 v118, v114, v114
	v_max_f32_e32 v114, v119, v119
	v_max_f32_e32 v115, v115, v115
	v_max_f32_e32 v116, 0, v116
	v_mul_f32_e32 v112, v112, v112
	v_max_f32_e32 v113, 0, v113
	v_max_f32_e32 v114, 0, v114
	v_max_f32_e32 v115, 0, v115
	v_mul_f32_e32 v116, v116, v116
	v_mul_f32_e32 v113, v113, v113
	v_mul_f32_e32 v114, v114, v114
	v_mul_f32_e32 v115, v115, v115
	v_cvt_pk_bf16_f32 v112, v116, v112
	v_max_f32_e32 v104, v104, v104
	v_cvt_pk_bf16_f32 v113, v113, v114
	v_cvt_pk_bf16_f32 v114, v120, v117
	v_cvt_pk_bf16_f32 v115, v118, v115
	global_store_dwordx4 v[144:145], v[112:115], off offset:256
	v_max_f32_e32 v104, 0, v104
	v_max_f32_e32 v105, v105, v105
	v_or_b32_e32 v112, 16, v152
	v_max_f32_e32 v106, v106, v106
	v_ashrrev_i32_e32 v113, 31, v112
	v_mul_f32_e32 v114, v104, v104
	v_max_f32_e32 v104, v109, v109
	v_max_f32_e32 v105, 0, v105
	v_max_f32_e32 v106, 0, v106
	v_lshlrev_b64 v[112:113], 13, v[112:113]
	v_max_f32_e32 v108, v108, v108
	v_max_f32_e32 v104, 0, v104
	v_mul_f32_e32 v109, v105, v105
	v_max_f32_e32 v105, v110, v110
	v_mul_f32_e32 v110, v106, v106
	v_max_f32_e32 v106, v111, v111
	v_max_f32_e32 v107, v107, v107
; __device__ __forceinline__ unsigned cvt_pk_bf16(float lo, float hi) { unsigned r; asm volatile("v_cvt_pk_bf16_f32 %0, %1, %2" : "=v"(r) : "v"(lo), "v"(hi)); return r; }
;     __device__ __forceinline__ void operator()(const f32x4 (&acc)[2][2][4][2], const Unit& u, int ui, int wr, int wc, int fr, int fq) const {
;     ...
; #pragma unroll
;         for (int ai = 0; ai < 2; ++ai)
; #pragma unroll
;             for (int m = 0; m < 4; ++m) { bf16_t* rowp = hid + (size_t)(row0 + ai * 128 + m * 16) * DFF + col0;
; #pragma unroll
;                 for (int bj = 0; bj < 2; ++bj) { f32x4 v0 = acc[ai][bj][m][0], v1 = acc[ai][bj][m][1];
; #pragma unroll
;                     for (int j = 0; j < 4; ++j) { const float a = fmaxf(v0[j], 0.f), b = fmaxf(v1[j], 0.f); v0[j] = a * a; v1[j] = b * b; }
;                     u32x4 w; w.x = cvt_pk_bf16(v0[0], v0[1]); w.y = cvt_pk_bf16(v0[2], v0[3]); w.z = cvt_pk_bf16(v1[0], v1[1]); w.w = cvt_pk_bf16(v1[2], v1[3]);
;                     *(u32x4*)(rowp + bj * 128) = w; } }
	v_lshl_add_u64 v[112:113], s[10:11], 0, v[112:113]
	v_max_f32_e32 v108, 0, v108
	v_mul_f32_e32 v104, v104, v104
	v_max_f32_e32 v105, 0, v105
	v_max_f32_e32 v106, 0, v106
	v_max_f32_e32 v107, 0, v107
	v_max_f32_e32 v96, v96, v96
	v_lshl_add_u64 v[112:113], v[112:113], 0, v[156:157]
	v_mul_f32_e32 v108, v108, v108
	v_mul_f32_e32 v105, v105, v105
	v_mul_f32_e32 v106, v106, v106
	v_mul_f32_e32 v107, v107, v107
	v_cvt_pk_bf16_f32 v104, v108, v104
	v_max_f32_e32 v96, 0, v96
	v_max_f32_e32 v97, v97, v97
	v_max_f32_e32 v98, v98, v98
	v_cvt_pk_bf16_f32 v105, v105, v106
	v_cvt_pk_bf16_f32 v106, v114, v109
	v_cvt_pk_bf16_f32 v107, v110, v107
	global_store_dwordx4 v[112:113], v[104:107], off
	v_max_f32_e32 v97, 0, v97
	v_max_f32_e32 v98, 0, v98
	v_mul_f32_e32 v104, v96, v96
	v_max_f32_e32 v96, v101, v101
	v_max_f32_e32 v100, v100, v100
	v_max_f32_e32 v96, 0, v96
	v_mul_f32_e32 v101, v97, v97
	v_max_f32_e32 v97, v102, v102
	v_mul_f32_e32 v102, v98, v98
	v_max_f32_e32 v98, v103, v103
	v_max_f32_e32 v99, v99, v99
	v_max_f32_e32 v100, 0, v100
	v_mul_f32_e32 v96, v96, v96
	v_max_f32_e32 v97, 0, v97
	v_max_f32_e32 v98, 0, v98
	v_max_f32_e32 v99, 0, v99
	v_mul_f32_e32 v100, v100, v100
	v_mul_f32_e32 v97, v97, v97
	v_mul_f32_e32 v98, v98, v98
	v_mul_f32_e32 v99, v99, v99
	v_cvt_pk_bf16_f32 v96, v100, v96
	v_max_f32_e32 v88, v88, v88
	v_cvt_pk_bf16_f32 v97, v97, v98
	v_cvt_pk_bf16_f32 v98, v104, v101
	v_cvt_pk_bf16_f32 v99, v102, v99
	global_store_dwordx4 v[112:113], v[96:99], off offset:256
	v_max_f32_e32 v88, 0, v88
	v_max_f32_e32 v89, v89, v89
	v_or_b32_e32 v96, 32, v152
	v_max_f32_e32 v90, v90, v90
	v_ashrrev_i32_e32 v97, 31, v96
	v_mul_f32_e32 v98, v88, v88
	v_max_f32_e32 v88, v93, v93
	v_max_f32_e32 v89, 0, v89
	v_max_f32_e32 v90, 0, v90
	v_lshlrev_b64 v[96:97], 13, v[96:97]
	v_max_f32_e32 v92, v92, v92
	v_max_f32_e32 v88, 0, v88
	v_mul_f32_e32 v93, v89, v89
	v_max_f32_e32 v89, v94, v94
	v_mul_f32_e32 v94, v90, v90
	v_max_f32_e32 v90, v95, v95
	v_max_f32_e32 v91, v91, v91
	v_lshl_add_u64 v[96:97], s[10:11], 0, v[96:97]
	v_max_f32_e32 v92, 0, v92
	v_mul_f32_e32 v88, v88, v88
	v_max_f32_e32 v89, 0, v89
	v_max_f32_e32 v90, 0, v90
	v_max_f32_e32 v91, 0, v91
	v_max_f32_e32 v80, v80, v80
	v_lshl_add_u64 v[96:97], v[96:97], 0, v[156:157]
	v_mul_f32_e32 v92, v92, v92
	v_mul_f32_e32 v89, v89, v89
	v_mul_f32_e32 v90, v90, v90
	v_mul_f32_e32 v91, v91, v91
	v_cvt_pk_bf16_f32 v88, v92, v88
	v_max_f32_e32 v80, 0, v80
	v_max_f32_e32 v81, v81, v81
	v_max_f32_e32 v82, v82, v82
	v_cvt_pk_bf16_f32 v89, v89, v90
	v_cvt_pk_bf16_f32 v90, v98, v93
	v_cvt_pk_bf16_f32 v91, v94, v91
	global_store_dwordx4 v[96:97], v[88:91], off
	v_max_f32_e32 v81, 0, v81
	v_max_f32_e32 v82, 0, v82
	v_mul_f32_e32 v88, v80, v80
	v_max_f32_e32 v80, v85, v85
	v_max_f32_e32 v84, v84, v84
	v_max_f32_e32 v80, 0, v80
	v_mul_f32_e32 v85, v81, v81
	v_max_f32_e32 v81, v86, v86
	v_mul_f32_e32 v86, v82, v82
	v_max_f32_e32 v82, v87, v87
	v_max_f32_e32 v83, v83, v83
	v_max_f32_e32 v84, 0, v84
	v_mul_f32_e32 v80, v80, v80
	v_max_f32_e32 v81, 0, v81
	v_max_f32_e32 v82, 0, v82
	v_max_f32_e32 v83, 0, v83
	v_mul_f32_e32 v84, v84, v84
	v_mul_f32_e32 v81, v81, v81
	v_mul_f32_e32 v82, v82, v82
	v_mul_f32_e32 v83, v83, v83
	v_cvt_pk_bf16_f32 v80, v84, v80
	v_max_f32_e32 v72, v72, v72
	v_cvt_pk_bf16_f32 v81, v81, v82
	v_cvt_pk_bf16_f32 v82, v88, v85
	v_cvt_pk_bf16_f32 v83, v86, v83
	global_store_dwordx4 v[96:97], v[80:83], off offset:256
	v_max_f32_e32 v72, 0, v72
	v_max_f32_e32 v73, v73, v73
	v_or_b32_e32 v80, 48, v152
	v_max_f32_e32 v74, v74, v74
	v_ashrrev_i32_e32 v81, 31, v80
	v_mul_f32_e32 v82, v72, v72
	v_max_f32_e32 v72, v77, v77
	v_max_f32_e32 v73, 0, v73
	v_max_f32_e32 v74, 0, v74
	v_lshlrev_b64 v[80:81], 13, v[80:81]
	v_max_f32_e32 v76, v76, v76
	v_max_f32_e32 v72, 0, v72
	v_mul_f32_e32 v77, v73, v73
	v_max_f32_e32 v73, v78, v78
	v_mul_f32_e32 v78, v74, v74
	v_max_f32_e32 v74, v79, v79
	v_max_f32_e32 v75, v75, v75
	v_lshl_add_u64 v[80:81], s[10:11], 0, v[80:81]
	v_max_f32_e32 v76, 0, v76
	v_mul_f32_e32 v72, v72, v72
	v_max_f32_e32 v73, 0, v73
	v_max_f32_e32 v74, 0, v74
	v_max_f32_e32 v75, 0, v75
	v_max_f32_e32 v64, v64, v64
	v_max_f32_e32 v65, v65, v65
	v_max_f32_e32 v66, v66, v66
	v_lshl_add_u64 v[80:81], v[80:81], 0, v[156:157]
	v_mul_f32_e32 v76, v76, v76
	v_mul_f32_e32 v73, v73, v73
	v_mul_f32_e32 v74, v74, v74
	v_mul_f32_e32 v75, v75, v75
	v_cvt_pk_bf16_f32 v72, v76, v72
	v_max_f32_e32 v64, 0, v64
	v_max_f32_e32 v65, 0, v65
	v_max_f32_e32 v66, 0, v66
	v_cvt_pk_bf16_f32 v73, v73, v74
	v_cvt_pk_bf16_f32 v74, v82, v77
	v_cvt_pk_bf16_f32 v75, v78, v75
	global_store_dwordx4 v[80:81], v[72:75], off
	v_max_f32_e32 v68, v68, v68
	v_max_f32_e32 v67, v67, v67
	v_mul_f32_e32 v72, v64, v64
	v_max_f32_e32 v64, v69, v69
	v_mul_f32_e32 v69, v65, v65
	v_max_f32_e32 v65, v70, v70
	v_mul_f32_e32 v70, v66, v66
	v_max_f32_e32 v66, v71, v71
	v_max_f32_e32 v64, 0, v64
	v_max_f32_e32 v65, 0, v65
	v_max_f32_e32 v66, 0, v66
	v_max_f32_e32 v68, 0, v68
	v_mul_f32_e32 v64, v64, v64
	v_mul_f32_e32 v65, v65, v65
	v_max_f32_e32 v67, 0, v67
	v_mul_f32_e32 v66, v66, v66
	v_max_f32_e32 v56, v56, v56
	v_mul_f32_e32 v68, v68, v68
	v_mul_f32_e32 v67, v67, v67
	v_cvt_pk_bf16_f32 v64, v68, v64
	v_cvt_pk_bf16_f32 v65, v65, v66
	v_cvt_pk_bf16_f32 v66, v72, v69
	v_max_f32_e32 v56, 0, v56
	v_max_f32_e32 v57, v57, v57
	v_max_f32_e32 v58, v58, v58
	v_cvt_pk_bf16_f32 v67, v70, v67
	global_store_dwordx4 v[80:81], v[64:67], off offset:256
	v_max_f32_e32 v60, v60, v60
	v_max_f32_e32 v57, 0, v57
	v_mul_f32_e32 v66, v56, v56
	v_max_f32_e32 v56, v61, v61
	v_max_f32_e32 v58, 0, v58
	v_max_f32_e32 v60, 0, v60
	v_max_f32_e32 v56, 0, v56
	v_mul_f32_e32 v61, v57, v57
; __device__ __forceinline__ unsigned cvt_pk_bf16(float lo, float hi) { unsigned r; asm volatile("v_cvt_pk_bf16_f32 %0, %1, %2" : "=v"(r) : "v"(lo), "v"(hi)); return r; }
;     __device__ __forceinline__ void operator()(const f32x4 (&acc)[2][2][4][2], const Unit& u, int ui, int wr, int wc, int fr, int fq) const {
;     ...
;         for (int ai = 0; ai < 2; ++ai)
; #pragma unroll
;             for (int m = 0; m < 4; ++m) { bf16_t* rowp = hid + (size_t)(row0 + ai * 128 + m * 16) * DFF + col0;
; #pragma unroll
;                 for (int bj = 0; bj < 2; ++bj) { f32x4 v0 = acc[ai][bj][m][0], v1 = acc[ai][bj][m][1];
; #pragma unroll
;                     for (int j = 0; j < 4; ++j) { const float a = fmaxf(v0[j], 0.f), b = fmaxf(v1[j], 0.f); v0[j] = a * a; v1[j] = b * b; }
;                     u32x4 w; w.x = cvt_pk_bf16(v0[0], v0[1]); w.y = cvt_pk_bf16(v0[2], v0[3]); w.z = cvt_pk_bf16(v1[0], v1[1]); w.w = cvt_pk_bf16(v1[2], v1[3]);
;                     *(u32x4*)(rowp + bj * 128) = w; } }
	v_max_f32_e32 v57, v62, v62
	v_mul_f32_e32 v62, v58, v58
	v_max_f32_e32 v58, v63, v63
	v_mul_f32_e32 v60, v60, v60
	v_mul_f32_e32 v56, v56, v56
	v_max_f32_e32 v57, 0, v57
	v_max_f32_e32 v58, 0, v58
	v_max_f32_e32 v59, v59, v59
	v_mul_f32_e32 v57, v57, v57
	v_max_f32_e32 v59, 0, v59
	v_mul_f32_e32 v58, v58, v58
	v_cvt_pk_bf16_f32 v56, v60, v56
	v_add_co_u32_e32 v60, vcc, s65, v144
	v_max_f32_e32 v48, v48, v48
	v_max_f32_e32 v49, v49, v49
	v_max_f32_e32 v50, v50, v50
	v_mul_f32_e32 v59, v59, v59
	v_cvt_pk_bf16_f32 v57, v57, v58
	v_cvt_pk_bf16_f32 v58, v66, v61
	v_addc_co_u32_e32 v61, vcc, 0, v145, vcc
	v_max_f32_e32 v48, 0, v48
	v_max_f32_e32 v49, 0, v49
	v_max_f32_e32 v50, 0, v50
	v_cvt_pk_bf16_f32 v59, v62, v59
	global_store_dwordx4 v[60:61], v[56:59], off
	v_max_f32_e32 v52, v52, v52
	v_max_f32_e32 v51, v51, v51
	v_mul_f32_e32 v56, v48, v48
	v_max_f32_e32 v48, v53, v53
	v_mul_f32_e32 v53, v49, v49
	v_max_f32_e32 v49, v54, v54
	v_mul_f32_e32 v54, v50, v50
	v_max_f32_e32 v50, v55, v55
	v_max_f32_e32 v48, 0, v48
	v_max_f32_e32 v49, 0, v49
	v_max_f32_e32 v50, 0, v50
	v_max_f32_e32 v52, 0, v52
	v_mul_f32_e32 v48, v48, v48
	v_mul_f32_e32 v49, v49, v49
	v_max_f32_e32 v51, 0, v51
	v_mul_f32_e32 v50, v50, v50
	v_max_f32_e32 v40, v40, v40
	v_lshl_add_u64 v[64:65], v[144:145], 0, s[14:15]
	v_mul_f32_e32 v52, v52, v52
	v_mul_f32_e32 v51, v51, v51
	v_cvt_pk_bf16_f32 v48, v52, v48
	v_cvt_pk_bf16_f32 v49, v49, v50
	v_cvt_pk_bf16_f32 v50, v56, v53
	v_max_f32_e32 v40, 0, v40
	v_max_f32_e32 v41, v41, v41
	v_max_f32_e32 v42, v42, v42
	v_cvt_pk_bf16_f32 v51, v54, v51
	global_store_dwordx4 v[64:65], v[48:51], off offset:256
	v_max_f32_e32 v44, v44, v44
	v_max_f32_e32 v41, 0, v41
	v_mul_f32_e32 v50, v40, v40
	v_max_f32_e32 v40, v45, v45
	v_max_f32_e32 v42, 0, v42
	v_max_f32_e32 v44, 0, v44
	v_max_f32_e32 v40, 0, v40
	v_mul_f32_e32 v45, v41, v41
	v_max_f32_e32 v41, v46, v46
	v_mul_f32_e32 v46, v42, v42
	v_max_f32_e32 v42, v47, v47
	v_mul_f32_e32 v44, v44, v44
	v_mul_f32_e32 v40, v40, v40
	v_max_f32_e32 v41, 0, v41
	v_max_f32_e32 v42, 0, v42
	v_max_f32_e32 v43, v43, v43
	v_mul_f32_e32 v41, v41, v41
	v_max_f32_e32 v43, 0, v43
	v_mul_f32_e32 v42, v42, v42
	v_cvt_pk_bf16_f32 v40, v44, v40
	v_add_co_u32_e32 v44, vcc, s66, v144
	v_max_f32_e32 v32, v32, v32
	v_max_f32_e32 v33, v33, v33
	v_max_f32_e32 v34, v34, v34
	v_mul_f32_e32 v43, v43, v43
	v_cvt_pk_bf16_f32 v41, v41, v42
	v_cvt_pk_bf16_f32 v42, v50, v45
	v_addc_co_u32_e32 v45, vcc, 0, v145, vcc
	v_max_f32_e32 v32, 0, v32
	v_max_f32_e32 v33, 0, v33
	v_max_f32_e32 v34, 0, v34
	v_cvt_pk_bf16_f32 v43, v46, v43
	global_store_dwordx4 v[44:45], v[40:43], off
	v_max_f32_e32 v36, v36, v36
	v_max_f32_e32 v35, v35, v35
	v_mul_f32_e32 v40, v32, v32
	v_max_f32_e32 v32, v37, v37
	v_mul_f32_e32 v37, v33, v33
	v_max_f32_e32 v33, v38, v38
	v_mul_f32_e32 v38, v34, v34
	v_max_f32_e32 v34, v39, v39
	v_max_f32_e32 v32, 0, v32
	v_max_f32_e32 v33, 0, v33
	v_max_f32_e32 v34, 0, v34
	v_max_f32_e32 v36, 0, v36
	v_mul_f32_e32 v32, v32, v32
	v_mul_f32_e32 v33, v33, v33
	v_max_f32_e32 v35, 0, v35
	v_mul_f32_e32 v34, v34, v34
	v_max_f32_e32 v24, v24, v24
	v_lshl_add_u64 v[48:49], v[144:145], 0, s[16:17]
	v_mul_f32_e32 v36, v36, v36
	v_mul_f32_e32 v35, v35, v35
	v_cvt_pk_bf16_f32 v32, v36, v32
	v_cvt_pk_bf16_f32 v33, v33, v34
	v_cvt_pk_bf16_f32 v34, v40, v37
	v_max_f32_e32 v24, 0, v24
	v_max_f32_e32 v25, v25, v25
	v_max_f32_e32 v26, v26, v26
	v_cvt_pk_bf16_f32 v35, v38, v35
	global_store_dwordx4 v[48:49], v[32:35], off offset:256
	v_max_f32_e32 v28, v28, v28
	v_max_f32_e32 v25, 0, v25
	v_mul_f32_e32 v34, v24, v24
	v_max_f32_e32 v24, v29, v29
; __device__ __forceinline__ unsigned cvt_pk_bf16(float lo, float hi) { unsigned r; asm volatile("v_cvt_pk_bf16_f32 %0, %1, %2" : "=v"(r) : "v"(lo), "v"(hi)); return r; }
; #define PG8_WAIT_V(n) asm volatile("s_waitcnt vmcnt(" #n ")" ::: "memory")
; #define PG8_BAR __builtin_amdgcn_s_barrier()
; template <class Epi, class Ptrs>
; __device__ __forceinline__ void gemm_phase(LAS unsigned char* lds, const int K, const StaticOrder& S, const Ptrs& P, const Epi& E) {
;     ...
;         if (!has_next) break;
; #pragma unroll
;         for (int a = 0; a < 2; ++a)
; #pragma unroll
;             for (int b = 0; b < 2; ++b)
; #pragma unroll
;                 for (int m = 0; m < 4; ++m)
; #pragma unroll
;                     for (int n = 0; n < 2; ++n) acc[a][b][m][n] = (f32x4){0.f, 0.f, 0.f, 0.f};
;         cur = nxt; cA = nA; cB = nB; ++ui;
;     }
;     PG8_WAIT_V(0);
;     if (wr == 0) PG8_BAR;
;     PG8_BAR;
;     __device__ __forceinline__ void operator()(const f32x4 (&acc)[2][2][4][2], const Unit& u, int ui, int wr, int wc, int fr, int fq) const {
;     ...
;         for (int ai = 0; ai < 2; ++ai)
; #pragma unroll
;             for (int m = 0; m < 4; ++m) { bf16_t* rowp = hid + (size_t)(row0 + ai * 128 + m * 16) * DFF + col0;
; #pragma unroll
;                 for (int bj = 0; bj < 2; ++bj) { f32x4 v0 = acc[ai][bj][m][0], v1 = acc[ai][bj][m][1];
; #pragma unroll
;                     for (int j = 0; j < 4; ++j) { const float a = fmaxf(v0[j], 0.f), b = fmaxf(v1[j], 0.f); v0[j] = a * a; v1[j] = b * b; }
;                     u32x4 w; w.x = cvt_pk_bf16(v0[0], v0[1]); w.y = cvt_pk_bf16(v0[2], v0[3]); w.z = cvt_pk_bf16(v1[0], v1[1]); w.w = cvt_pk_bf16(v1[2], v1[3]);
;                     *(u32x4*)(rowp + bj * 128) = w; } }
	v_max_f32_e32 v26, 0, v26
	v_max_f32_e32 v28, 0, v28
	v_max_f32_e32 v24, 0, v24
	v_mul_f32_e32 v29, v25, v25
	v_max_f32_e32 v25, v30, v30
	v_mul_f32_e32 v30, v26, v26
	v_max_f32_e32 v26, v31, v31
	v_mul_f32_e32 v28, v28, v28
	v_mul_f32_e32 v24, v24, v24
	v_max_f32_e32 v25, 0, v25
	v_max_f32_e32 v26, 0, v26
	v_max_f32_e32 v27, v27, v27
	v_mul_f32_e32 v25, v25, v25
	v_max_f32_e32 v27, 0, v27
	v_mul_f32_e32 v26, v26, v26
	v_cvt_pk_bf16_f32 v24, v28, v24
	v_add_co_u32_e32 v28, vcc, s67, v144
	v_max_f32_e32 v16, v16, v16
	v_max_f32_e32 v17, v17, v17
	v_max_f32_e32 v18, v18, v18
	v_mul_f32_e32 v27, v27, v27
	v_cvt_pk_bf16_f32 v25, v25, v26
	v_cvt_pk_bf16_f32 v26, v34, v29
	v_addc_co_u32_e32 v29, vcc, 0, v145, vcc
	v_max_f32_e32 v16, 0, v16
	v_max_f32_e32 v17, 0, v17
	v_max_f32_e32 v18, 0, v18
	v_cvt_pk_bf16_f32 v27, v30, v27
	global_store_dwordx4 v[28:29], v[24:27], off
	v_max_f32_e32 v20, v20, v20
	v_max_f32_e32 v19, v19, v19
	v_mul_f32_e32 v24, v16, v16
	v_max_f32_e32 v16, v21, v21
	v_mul_f32_e32 v21, v17, v17
	v_max_f32_e32 v17, v22, v22
	v_mul_f32_e32 v22, v18, v18
	v_max_f32_e32 v18, v23, v23
	v_max_f32_e32 v16, 0, v16
	v_max_f32_e32 v17, 0, v17
	v_max_f32_e32 v18, 0, v18
	v_max_f32_e32 v20, 0, v20
	v_mul_f32_e32 v16, v16, v16
	v_mul_f32_e32 v17, v17, v17
	v_max_f32_e32 v19, 0, v19
	v_mul_f32_e32 v18, v18, v18
	v_max_f32_e32 v8, v8, v8
	v_lshl_add_u64 v[32:33], v[144:145], 0, s[18:19]
	v_mul_f32_e32 v20, v20, v20
	v_mul_f32_e32 v19, v19, v19
	v_cvt_pk_bf16_f32 v16, v20, v16
	v_cvt_pk_bf16_f32 v17, v17, v18
	v_cvt_pk_bf16_f32 v18, v24, v21
	v_max_f32_e32 v8, 0, v8
	v_max_f32_e32 v9, v9, v9
	v_max_f32_e32 v10, v10, v10
	v_cvt_pk_bf16_f32 v19, v22, v19
	global_store_dwordx4 v[32:33], v[16:19], off offset:256
	v_max_f32_e32 v12, v12, v12
	v_max_f32_e32 v9, 0, v9
	v_mul_f32_e32 v18, v8, v8
	v_max_f32_e32 v8, v13, v13
	v_max_f32_e32 v10, 0, v10
	v_max_f32_e32 v12, 0, v12
	v_max_f32_e32 v8, 0, v8
	v_mul_f32_e32 v13, v9, v9
	v_max_f32_e32 v9, v14, v14
	v_mul_f32_e32 v14, v10, v10
	v_max_f32_e32 v10, v15, v15
	v_mul_f32_e32 v12, v12, v12
	v_mul_f32_e32 v8, v8, v8
	v_max_f32_e32 v9, 0, v9
	v_max_f32_e32 v10, 0, v10
	v_max_f32_e32 v11, v11, v11
	v_mul_f32_e32 v9, v9, v9
	v_max_f32_e32 v11, 0, v11
	v_mul_f32_e32 v10, v10, v10
	v_cvt_pk_bf16_f32 v8, v12, v8
	v_add_co_u32_e32 v12, vcc, s68, v144
	v_max_f32_e32 v0, v0, v0
	v_max_f32_e32 v1, v1, v1
	v_max_f32_e32 v2, v2, v2
	v_mul_f32_e32 v11, v11, v11
	v_cvt_pk_bf16_f32 v9, v9, v10
	v_cvt_pk_bf16_f32 v10, v18, v13
	v_addc_co_u32_e32 v13, vcc, 0, v145, vcc
	v_max_f32_e32 v0, 0, v0
	v_max_f32_e32 v1, 0, v1
	v_max_f32_e32 v2, 0, v2
	v_cvt_pk_bf16_f32 v11, v14, v11
	global_store_dwordx4 v[12:13], v[8:11], off
	v_max_f32_e32 v3, v3, v3
	v_max_f32_e32 v4, v4, v4
	v_mul_f32_e32 v8, v0, v0
	v_max_f32_e32 v0, v5, v5
	v_mul_f32_e32 v5, v1, v1
	v_max_f32_e32 v1, v6, v6
	v_mul_f32_e32 v6, v2, v2
	v_max_f32_e32 v2, v7, v7
	v_max_f32_e32 v0, 0, v0
	v_max_f32_e32 v1, 0, v1
	v_max_f32_e32 v2, 0, v2
	v_max_f32_e32 v3, 0, v3
	v_lshl_add_u64 v[16:17], v[144:145], 0, s[20:21]
	v_max_f32_e32 v4, 0, v4
	v_mul_f32_e32 v0, v0, v0
	v_mul_f32_e32 v1, v1, v1
	v_mul_f32_e32 v2, v2, v2
	v_mul_f32_e32 v3, v3, v3
	s_and_b64 vcc, exec, s[4:5]
	s_mov_b32 s69, s22
	s_mov_b32 s38, s24
	s_mov_b64 s[40:41], s[0:1]
	s_mov_b64 s[42:43], s[36:37]
	v_mul_f32_e32 v4, v4, v4
	v_cvt_pk_bf16_f32 v0, v4, v0
	v_cvt_pk_bf16_f32 v1, v1, v2
	v_cvt_pk_bf16_f32 v2, v8, v5
	v_cvt_pk_bf16_f32 v3, v6, v3
	global_store_dwordx4 v[16:17], v[0:3], off offset:256
	s_cbranch_vccz .LBB0_428
	s_waitcnt vmcnt(0)
	s_cmpk_gt_u32 s46, 0xff
	s_cbranch_scc1 .LBB0_437
	s_barrier

; #define PG8_STAGE(bufoff, gbase, voff) do { _Pragma("unroll") for (int _i = 0; _i < 2; ++_i) \
;         __builtin_amdgcn_global_load_lds((const unsigned*)((const char*)(gbase) + (voff)[_i]), (LAS unsigned*)(lds + (bufoff) + ldsw + _i * 8192), 16, 0, 0); } while (0)
; #define PG8_LDA(dst, b, h) do { _Pragma("unroll") for (int m = 0; m < 4; ++m) _Pragma("unroll") for (int k = 0; k < 2; ++k) dst[m][k] = *(const LAS bf16x8*)(lds + PG8_SA(b, h) + aoff + m * 2048 + k * 1024); } while (0)
; #define PG8_LDB(dst, b, h) do { _Pragma("unroll") for (int n = 0; n < 2; ++n) _Pragma("unroll") for (int k = 0; k < 2; ++k) dst[n][k] = *(const LAS bf16x8*)(lds + PG8_SB(b, h) + boff + n * 2048 + k * 1024); } while (0)
; #define PG8_MMA(ai, bj, At, Bt) do { __builtin_amdgcn_s_setprio(1); _Pragma("unroll") for (int m = 0; m < 4; ++m) _Pragma("unroll") for (int n = 0; n < 2; ++n) _Pragma("unroll") for (int k = 0; k < 2; ++k) \
;         acc[ai][bj][m][n] = __builtin_amdgcn_mfma_f32_16x16x32_bf16(Bt[n][k], At[m][k], acc[ai][bj][m][n], 0, 0, 0); __builtin_amdgcn_s_setprio(0); } while (0)
; #define PG8_WAIT_L(n) asm volatile("s_waitcnt lgkmcnt(" #n ")" ::: "memory")
; #define PG8_BAR __builtin_amdgcn_s_barrier()
; #define PG8_SCHED __builtin_amdgcn_sched_barrier(0)
; template <class Epi, class Ptrs>
; __device__ __forceinline__ void gemm_phase(LAS unsigned char* lds, const int K, const StaticOrder& S, const Ptrs& P, const Epi& E) {
;     ...
;             const bool last = (t == nt - 2);
;             const char* a1 = cA + (size_t)(t + 1) * kstep;
;             const char* a2 = last ? nA : cA + (size_t)(t + 2) * kstep; const char* b2 = last ? nB : cB + (size_t)(t + 2) * kstep;
;             const char* a3 = a2 + kstep; const char* b3 = b2 + kstep;
;             PG8_LDB(B0, 0, 0); PG8_SCHED; PG8_LDA(At, 0, 0); PG8_STAGE(PG8_SA(1, 1), a1 + hstep, voffA);
;             PG8_WAIT_L(8); PG8_BAR; PG8_WAIT_L(0); PG8_MMA(0, 0, At, B0); PG8_BAR; PG8_SCHED;
;             PG8_LDB(B1, 0, 1); PG8_STAGE(PG8_SB(0, 0), b2, voffB);
;             PG8_BAR; PG8_WAIT_L(0); PG8_MMA(0, 1, At, B1); PG8_BAR;
;             PG8_LDA(At, 0, 1); PG8_STAGE(PG8_SA(0, 0), a2, voffA);
;             PG8_BAR; PG8_WAIT_L(0); PG8_MMA(1, 0, At, B0); PG8_BAR; PG8_SCHED;
.LBB0_522:
	ds_read_b128 v[128:131], v193
	ds_read_b128 v[132:135], v193 offset:1024
	ds_read_b128 v[136:139], v193 offset:2048
	ds_read_b128 v[140:143], v193 offset:3072
	s_add_u32 s22, s20, 0xfff00080
	s_addc_u32 s23, s21, -1
	s_cmp_eq_u32 s46, 60
	s_cselect_b32 s25, s5, s23
	s_cselect_b32 s24, s4, s22
	s_cselect_b32 s23, s15, s13
	s_cselect_b32 s22, s14, s11
	v_lshl_add_u64 v[184:185], s[20:21], 0, v[168:169]
	s_add_i32 m0, s17, 0xc000
	ds_read_b128 v[144:147], v194
	ds_read_b128 v[148:151], v194 offset:1024
	ds_read_b128 v[152:155], v194 offset:2048
	ds_read_b128 v[156:159], v194 offset:3072
	ds_read_b128 v[176:179], v194 offset:4096
	ds_read_b128 v[180:183], v194 offset:5120
	ds_read_b128 v[196:199], v194 offset:6144
	ds_read_b128 v[200:203], v194 offset:7168
	global_load_lds_dwordx4 v[184:185], off
	v_lshl_add_u64 v[184:185], s[20:21], 0, v[170:171]
	s_add_i32 m0, s17, 0xe000
	s_nop 0
	global_load_lds_dwordx4 v[184:185], off
	s_waitcnt lgkmcnt(8)
	s_barrier
	s_waitcnt lgkmcnt(0)
	s_setprio 1
	s_waitcnt lgkmcnt(0)
	v_mfma_f32_16x16x32_bf16 v[124:127], v[128:131], v[144:147], v[124:127]
	v_mfma_f32_16x16x32_bf16 v[124:127], v[132:135], v[148:151], v[124:127]
	v_mfma_f32_16x16x32_bf16 v[112:115], v[132:135], v[156:159], v[112:115]
	v_mfma_f32_16x16x32_bf16 v[112:115], v[128:131], v[152:155], v[112:115]
	v_mfma_f32_16x16x32_bf16 v[92:95], v[128:131], v[176:179], v[92:95]
	v_mfma_f32_16x16x32_bf16 v[92:95], v[132:135], v[180:183], v[92:95]
	v_mfma_f32_16x16x32_bf16 v[76:79], v[132:135], v[200:203], v[76:79]
	v_mfma_f32_16x16x32_bf16 v[76:79], v[128:131], v[196:199], v[76:79]
	v_mfma_f32_16x16x32_bf16 v[72:75], v[136:139], v[196:199], v[72:75]
	v_mfma_f32_16x16x32_bf16 v[72:75], v[140:143], v[200:203], v[72:75]
	v_mfma_f32_16x16x32_bf16 v[88:91], v[140:143], v[180:183], v[88:91]
	v_mfma_f32_16x16x32_bf16 v[88:91], v[136:139], v[176:179], v[88:91]
	v_mfma_f32_16x16x32_bf16 v[104:107], v[136:139], v[152:155], v[104:107]
	v_mfma_f32_16x16x32_bf16 v[104:107], v[140:143], v[156:159], v[104:107]
	v_mfma_f32_16x16x32_bf16 v[120:123], v[140:143], v[148:151], v[120:123]
	v_mfma_f32_16x16x32_bf16 v[120:123], v[136:139], v[144:147], v[120:123]
	s_setprio 0
	s_barrier
	s_add_i32 s47, s42, s34
	v_lshl_add_u64 v[184:185], s[22:23], 0, v[162:163]
	s_mov_b32 m0, s47
	ds_read_b128 v[204:207], v195
	ds_read_b128 v[208:211], v195 offset:1024
	ds_read_b128 v[212:215], v195 offset:2048
	ds_read_b128 v[216:219], v195 offset:3072
	global_load_lds_dwordx4 v[184:185], off
	v_lshl_add_u64 v[220:221], s[22:23], 0, v[166:167]
	s_add_i32 m0, s47, 0x2000
	s_nop 0
	global_load_lds_dwordx4 v[220:221], off
	s_barrier
	s_waitcnt lgkmcnt(0)
	s_setprio 1
	s_waitcnt lgkmcnt(0)
	v_mfma_f32_16x16x32_bf16 v[116:119], v[204:207], v[144:147], v[116:119]
	v_mfma_f32_16x16x32_bf16 v[116:119], v[208:211], v[148:151], v[116:119]
	v_mfma_f32_16x16x32_bf16 v[100:103], v[208:211], v[156:159], v[100:103]
	v_mfma_f32_16x16x32_bf16 v[100:103], v[204:207], v[152:155], v[100:103]
	v_mfma_f32_16x16x32_bf16 v[84:87], v[204:207], v[176:179], v[84:87]
	v_mfma_f32_16x16x32_bf16 v[84:87], v[208:211], v[180:183], v[84:87]
	v_mfma_f32_16x16x32_bf16 v[68:71], v[208:211], v[200:203], v[68:71]
	v_mfma_f32_16x16x32_bf16 v[68:71], v[204:207], v[196:199], v[68:71]
	v_mfma_f32_16x16x32_bf16 v[64:67], v[212:215], v[196:199], v[64:67]
	v_mfma_f32_16x16x32_bf16 v[64:67], v[216:219], v[200:203], v[64:67]
	v_mfma_f32_16x16x32_bf16 v[80:83], v[216:219], v[180:183], v[80:83]
	v_mfma_f32_16x16x32_bf16 v[80:83], v[212:215], v[176:179], v[80:83]
	v_mfma_f32_16x16x32_bf16 v[96:99], v[212:215], v[152:155], v[96:99]
	v_mfma_f32_16x16x32_bf16 v[96:99], v[216:219], v[156:159], v[96:99]
	v_mfma_f32_16x16x32_bf16 v[108:111], v[216:219], v[148:151], v[108:111]
	v_mfma_f32_16x16x32_bf16 v[108:111], v[212:215], v[144:147], v[108:111]
	s_setprio 0
	s_mov_b32 m0, s17
	v_lshl_add_u64 v[222:223], s[24:25], 0, v[160:161]
	s_barrier
	ds_read_b128 v[144:147], v194 offset:16384
	ds_read_b128 v[148:151], v194 offset:17408
	ds_read_b128 v[152:155], v194 offset:18432
	ds_read_b128 v[156:159], v194 offset:19456
	ds_read_b128 v[176:179], v194 offset:20480
	ds_read_b128 v[180:183], v194 offset:21504
	ds_read_b128 v[196:199], v194 offset:22528
	ds_read_b128 v[200:203], v194 offset:23552
	global_load_lds_dwordx4 v[222:223], off
	v_lshl_add_u64 v[224:225], s[24:25], 0, v[164:165]
	s_mov_b32 m0, s19
	s_nop 0
	global_load_lds_dwordx4 v[224:225], off
	s_barrier
	s_waitcnt lgkmcnt(0)
	s_setprio 1
	s_waitcnt lgkmcnt(0)
	v_mfma_f32_16x16x32_bf16 v[60:63], v[128:131], v[144:147], v[60:63]
	v_mfma_f32_16x16x32_bf16 v[60:63], v[132:135], v[148:151], v[60:63]
	v_mfma_f32_16x16x32_bf16 v[48:51], v[132:135], v[156:159], v[48:51]
	v_mfma_f32_16x16x32_bf16 v[48:51], v[128:131], v[152:155], v[48:51]
	v_mfma_f32_16x16x32_bf16 v[32:35], v[128:131], v[176:179], v[32:35]
	v_mfma_f32_16x16x32_bf16 v[32:35], v[132:135], v[180:183], v[32:35]
	v_mfma_f32_16x16x32_bf16 v[16:19], v[132:135], v[200:203], v[16:19]
	v_mfma_f32_16x16x32_bf16 v[16:19], v[128:131], v[196:199], v[16:19]
	v_mfma_f32_16x16x32_bf16 v[8:11], v[136:139], v[196:199], v[8:11]
	v_mfma_f32_16x16x32_bf16 v[8:11], v[140:143], v[200:203], v[8:11]
	v_mfma_f32_16x16x32_bf16 v[24:27], v[140:143], v[180:183], v[24:27]
	v_mfma_f32_16x16x32_bf16 v[24:27], v[136:139], v[176:179], v[24:27]
	v_mfma_f32_16x16x32_bf16 v[40:43], v[136:139], v[152:155], v[40:43]
	v_mfma_f32_16x16x32_bf16 v[40:43], v[140:143], v[156:159], v[40:43]
	v_mfma_f32_16x16x32_bf16 v[56:59], v[140:143], v[148:151], v[56:59]
	v_mfma_f32_16x16x32_bf16 v[56:59], v[136:139], v[144:147], v[56:59]
	s_setprio 0
	s_barrier
; #define PG8_STAGE(bufoff, gbase, voff) do { _Pragma("unroll") for (int _i = 0; _i < 2; ++_i) \
;         __builtin_amdgcn_global_load_lds((const unsigned*)((const char*)(gbase) + (voff)[_i]), (LAS unsigned*)(lds + (bufoff) + ldsw + _i * 8192), 16, 0, 0); } while (0)
; #define PG8_LDA(dst, b, h) do { _Pragma("unroll") for (int m = 0; m < 4; ++m) _Pragma("unroll") for (int k = 0; k < 2; ++k) dst[m][k] = *(const LAS bf16x8*)(lds + PG8_SA(b, h) + aoff + m * 2048 + k * 1024); } while (0)
; #define PG8_LDB(dst, b, h) do { _Pragma("unroll") for (int n = 0; n < 2; ++n) _Pragma("unroll") for (int k = 0; k < 2; ++k) dst[n][k] = *(const LAS bf16x8*)(lds + PG8_SB(b, h) + boff + n * 2048 + k * 1024); } while (0)
; #define PG8_MMA(ai, bj, At, Bt) do { __builtin_amdgcn_s_setprio(1); _Pragma("unroll") for (int m = 0; m < 4; ++m) _Pragma("unroll") for (int n = 0; n < 2; ++n) _Pragma("unroll") for (int k = 0; k < 2; ++k) \
;         acc[ai][bj][m][n] = __builtin_amdgcn_mfma_f32_16x16x32_bf16(Bt[n][k], At[m][k], acc[ai][bj][m][n], 0, 0, 0); __builtin_amdgcn_s_setprio(0); } while (0)
; #define PG8_WAIT_V(n) asm volatile("s_waitcnt vmcnt(" #n ")" ::: "memory")
; #define PG8_WAIT_L(n) asm volatile("s_waitcnt lgkmcnt(" #n ")" ::: "memory")
; #define PG8_BAR __builtin_amdgcn_s_barrier()
; #define PG8_SCHED __builtin_amdgcn_sched_barrier(0)
; template <class Epi, class Ptrs>
; __device__ __forceinline__ void gemm_phase(LAS unsigned char* lds, const int K, const StaticOrder& S, const Ptrs& P, const Epi& E) {
;     ...
;             PG8_STAGE(PG8_SB(0, 1), b2 + hstep, voffB);
;             PG8_WAIT_V(6); PG8_BAR; PG8_MMA(1, 1, At, B1); PG8_BAR;
;             PG8_LDB(B0, 1, 0); PG8_SCHED; PG8_LDA(At, 1, 0); PG8_STAGE(PG8_SA(0, 1), a2 + hstep, voffA);
;             PG8_WAIT_L(8); PG8_BAR; PG8_WAIT_L(0); PG8_MMA(0, 0, At, B0); PG8_BAR; PG8_SCHED;
;             PG8_LDB(B1, 1, 1); PG8_STAGE(PG8_SB(1, 0), b3, voffB);
;             PG8_BAR; PG8_WAIT_L(0); PG8_MMA(0, 1, At, B1); PG8_BAR;
;             PG8_LDA(At, 1, 1); PG8_STAGE(PG8_SA(1, 0), a3, voffA);
;             PG8_BAR; PG8_WAIT_L(0); PG8_MMA(1, 0, At, B0); PG8_BAR; PG8_SCHED;
	s_add_u32 s48, s22, 0x100000
	s_addc_u32 s49, s23, 0
	s_add_i32 s47, s43, s34
	v_lshl_add_u64 v[128:129], s[48:49], 0, v[162:163]
	s_mov_b32 m0, s47
	s_nop 0
	global_load_lds_dwordx4 v[128:129], off
	v_lshl_add_u64 v[128:129], s[48:49], 0, v[166:167]
	s_add_i32 m0, s47, 0x2000
	s_nop 0
	global_load_lds_dwordx4 v[128:129], off
	s_waitcnt vmcnt(6)
	s_barrier
	s_setprio 1
	v_mfma_f32_16x16x32_bf16 v[52:55], v[204:207], v[144:147], v[52:55]
	v_mfma_f32_16x16x32_bf16 v[52:55], v[208:211], v[148:151], v[52:55]
	v_mfma_f32_16x16x32_bf16 v[36:39], v[208:211], v[156:159], v[36:39]
	v_mfma_f32_16x16x32_bf16 v[36:39], v[204:207], v[152:155], v[36:39]
	v_mfma_f32_16x16x32_bf16 v[20:23], v[204:207], v[176:179], v[20:23]
	v_mfma_f32_16x16x32_bf16 v[20:23], v[208:211], v[180:183], v[20:23]
	v_mfma_f32_16x16x32_bf16 v[4:7], v[208:211], v[200:203], v[4:7]
	v_mfma_f32_16x16x32_bf16 v[4:7], v[204:207], v[196:199], v[4:7]
	v_mfma_f32_16x16x32_bf16 v[0:3], v[212:215], v[196:199], v[0:3]
	v_mfma_f32_16x16x32_bf16 v[0:3], v[216:219], v[200:203], v[0:3]
	v_mfma_f32_16x16x32_bf16 v[12:15], v[216:219], v[180:183], v[12:15]
	v_mfma_f32_16x16x32_bf16 v[12:15], v[212:215], v[176:179], v[12:15]
	v_mfma_f32_16x16x32_bf16 v[28:31], v[212:215], v[152:155], v[28:31]
	v_mfma_f32_16x16x32_bf16 v[28:31], v[216:219], v[156:159], v[28:31]
	v_mfma_f32_16x16x32_bf16 v[44:47], v[216:219], v[148:151], v[44:47]
	v_mfma_f32_16x16x32_bf16 v[44:47], v[212:215], v[144:147], v[44:47]
	s_setprio 0
	s_add_i32 s47, 0, 0x18000
	v_add_u32_e32 v140, s47, v187
	s_barrier
	ds_read_b128 v[128:131], v140
	ds_read_b128 v[132:135], v140 offset:1024
	ds_read_b128 v[136:139], v140 offset:2048
	ds_read_b128 v[140:143], v140 offset:3072
	s_add_u32 s24, s24, 0x100000
	s_addc_u32 s25, s25, 0
	s_mov_b32 m0, s40
	v_lshl_add_u64 v[204:205], s[24:25], 0, v[160:161]
	ds_read_b128 v[144:147], v194 offset:32768
	ds_read_b128 v[148:151], v194 offset:33792
	ds_read_b128 v[152:155], v194 offset:34816
	ds_read_b128 v[156:159], v194 offset:35840
	ds_read_b128 v[176:179], v194 offset:36864
	ds_read_b128 v[180:183], v194 offset:37888
	ds_read_b128 v[196:199], v194 offset:38912
	ds_read_b128 v[200:203], v194 offset:39936
	global_load_lds_dwordx4 v[204:205], off
	v_lshl_add_u64 v[204:205], s[24:25], 0, v[164:165]
	s_mov_b32 m0, s41
	s_nop 0
	global_load_lds_dwordx4 v[204:205], off
	s_waitcnt lgkmcnt(8)
	s_barrier
	s_waitcnt lgkmcnt(0)
	s_setprio 1
	s_waitcnt lgkmcnt(0)
	v_mfma_f32_16x16x32_bf16 v[124:127], v[128:131], v[144:147], v[124:127]
	v_mfma_f32_16x16x32_bf16 v[124:127], v[132:135], v[148:151], v[124:127]
	v_mfma_f32_16x16x32_bf16 v[112:115], v[132:135], v[156:159], v[112:115]
	v_mfma_f32_16x16x32_bf16 v[112:115], v[128:131], v[152:155], v[112:115]
	v_mfma_f32_16x16x32_bf16 v[92:95], v[128:131], v[176:179], v[92:95]
	v_mfma_f32_16x16x32_bf16 v[92:95], v[132:135], v[180:183], v[92:95]
	v_mfma_f32_16x16x32_bf16 v[76:79], v[132:135], v[200:203], v[76:79]
	v_mfma_f32_16x16x32_bf16 v[76:79], v[128:131], v[196:199], v[76:79]
	v_mfma_f32_16x16x32_bf16 v[72:75], v[136:139], v[196:199], v[72:75]
	v_mfma_f32_16x16x32_bf16 v[72:75], v[140:143], v[200:203], v[72:75]
	v_mfma_f32_16x16x32_bf16 v[88:91], v[140:143], v[180:183], v[88:91]
	v_mfma_f32_16x16x32_bf16 v[88:91], v[136:139], v[176:179], v[88:91]
	v_mfma_f32_16x16x32_bf16 v[104:107], v[136:139], v[152:155], v[104:107]
	v_mfma_f32_16x16x32_bf16 v[104:107], v[140:143], v[156:159], v[104:107]
	v_mfma_f32_16x16x32_bf16 v[120:123], v[140:143], v[148:151], v[120:123]
	v_mfma_f32_16x16x32_bf16 v[120:123], v[136:139], v[144:147], v[120:123]
	s_setprio 0
	s_barrier
	s_add_i32 s24, 0, 0x1c000
	s_add_i32 s25, s47, s34
	v_add_u32_e32 v216, s24, v187
	v_lshl_add_u64 v[184:185], v[184:185], 0, s[8:9]
	s_mov_b32 m0, s25
	ds_read_b128 v[204:207], v216
	ds_read_b128 v[208:211], v216 offset:1024
	ds_read_b128 v[212:215], v216 offset:2048
	ds_read_b128 v[216:219], v216 offset:3072
	global_load_lds_dwordx4 v[184:185], off
	v_lshl_add_u64 v[184:185], v[220:221], 0, s[8:9]
	s_add_i32 m0, s25, 0x2000
	s_nop 0
	global_load_lds_dwordx4 v[184:185], off
	s_barrier
	s_waitcnt lgkmcnt(0)
	s_setprio 1
	s_waitcnt lgkmcnt(0)
	v_mfma_f32_16x16x32_bf16 v[116:119], v[204:207], v[144:147], v[116:119]
	v_mfma_f32_16x16x32_bf16 v[116:119], v[208:211], v[148:151], v[116:119]
	v_mfma_f32_16x16x32_bf16 v[100:103], v[208:211], v[156:159], v[100:103]
	v_mfma_f32_16x16x32_bf16 v[100:103], v[204:207], v[152:155], v[100:103]
	v_mfma_f32_16x16x32_bf16 v[84:87], v[204:207], v[176:179], v[84:87]
	v_mfma_f32_16x16x32_bf16 v[84:87], v[208:211], v[180:183], v[84:87]
	v_mfma_f32_16x16x32_bf16 v[68:71], v[208:211], v[200:203], v[68:71]
	v_mfma_f32_16x16x32_bf16 v[68:71], v[204:207], v[196:199], v[68:71]
	v_mfma_f32_16x16x32_bf16 v[64:67], v[212:215], v[196:199], v[64:67]
	v_mfma_f32_16x16x32_bf16 v[64:67], v[216:219], v[200:203], v[64:67]
	v_mfma_f32_16x16x32_bf16 v[80:83], v[216:219], v[180:183], v[80:83]
	v_mfma_f32_16x16x32_bf16 v[80:83], v[212:215], v[176:179], v[80:83]
	v_mfma_f32_16x16x32_bf16 v[96:99], v[212:215], v[152:155], v[96:99]
	v_mfma_f32_16x16x32_bf16 v[96:99], v[216:219], v[156:159], v[96:99]
	v_mfma_f32_16x16x32_bf16 v[108:111], v[216:219], v[148:151], v[108:111]
	v_mfma_f32_16x16x32_bf16 v[108:111], v[212:215], v[144:147], v[108:111]
	s_setprio 0
	s_mov_b32 m0, s28
	v_lshl_add_u64 v[184:185], v[222:223], 0, s[8:9]
	s_barrier
	ds_read_b128 v[144:147], v194 offset:49152
	ds_read_b128 v[148:151], v194 offset:50176
	ds_read_b128 v[152:155], v194 offset:51200
	ds_read_b128 v[156:159], v194 offset:52224
	ds_read_b128 v[176:179], v194 offset:53248
	ds_read_b128 v[180:183], v194 offset:54272
	ds_read_b128 v[196:199], v194 offset:55296
	ds_read_b128 v[200:203], v194 offset:56320
	global_load_lds_dwordx4 v[184:185], off
	v_lshl_add_u64 v[184:185], v[224:225], 0, s[8:9]
	s_mov_b32 m0, s29
	s_nop 0
	global_load_lds_dwordx4 v[184:185], off
	s_barrier
; #define PG8_STAGE(bufoff, gbase, voff) do { _Pragma("unroll") for (int _i = 0; _i < 2; ++_i) \
;         __builtin_amdgcn_global_load_lds((const unsigned*)((const char*)(gbase) + (voff)[_i]), (LAS unsigned*)(lds + (bufoff) + ldsw + _i * 8192), 16, 0, 0); } while (0)
; #define PG8_MMA(ai, bj, At, Bt) do { __builtin_amdgcn_s_setprio(1); _Pragma("unroll") for (int m = 0; m < 4; ++m) _Pragma("unroll") for (int n = 0; n < 2; ++n) _Pragma("unroll") for (int k = 0; k < 2; ++k) \
;         acc[ai][bj][m][n] = __builtin_amdgcn_mfma_f32_16x16x32_bf16(Bt[n][k], At[m][k], acc[ai][bj][m][n], 0, 0, 0); __builtin_amdgcn_s_setprio(0); } while (0)
; #define PG8_WAIT_V(n) asm volatile("s_waitcnt vmcnt(" #n ")" ::: "memory")
; #define PG8_WAIT_L(n) asm volatile("s_waitcnt lgkmcnt(" #n ")" ::: "memory")
; #define PG8_BAR __builtin_amdgcn_s_barrier()
; #define PG8_SCHED __builtin_amdgcn_sched_barrier(0)
; template <class Epi, class Ptrs>
; __device__ __forceinline__ void gemm_phase(LAS unsigned char* lds, const int K, const StaticOrder& S, const Ptrs& P, const Epi& E) {
;     ...
;             PG8_BAR; PG8_WAIT_L(0); PG8_MMA(1, 0, At, B0); PG8_BAR; PG8_SCHED;
;             PG8_STAGE(PG8_SB(1, 1), b3 + hstep, voffB);
;             PG8_WAIT_V(6); PG8_BAR; PG8_MMA(1, 1, At, B1); PG8_BAR;
;     __device__ __forceinline__ void operator()(const f32x4 (&acc)[2][2][4][2], const Unit& u, int ui, int wr, int wc, int fr, int fq) const {
;         const int rl0 = wr * 64 + fr, col0 = u.pn * 256 + wc * 32 + 8 * fq;
;         u32x4 xv[2][4][2];
; #pragma unroll
;         for (int ai = 0; ai < 2; ++ai)
; #pragma unroll
;             for (int m = 0; m < 4; ++m)
; #pragma unroll
;                 for (int bj = 0; bj < 2; ++bj) xv[ai][m][bj] = *(const u32x4*)(xb + (size_t)(u.pm * 256 + rl0 + ai * 128 + m * 16) * DM + col0 + bj * 128);
; #pragma unroll
;         for (int ai = 0; ai < 2; ++ai)
; #pragma unroll
;             for (int m = 0; m < 4; ++m) { const int rl = rl0 + ai * 128 + m * 16; float* rowp = out + (size_t)(u.pm * 256 + rl) * DM + col0;
;                 const float r2 = tab[ui * 256 + rl];
	s_waitcnt lgkmcnt(0)
	s_setprio 1
	s_waitcnt lgkmcnt(0)
	v_mfma_f32_16x16x32_bf16 v[60:63], v[128:131], v[144:147], v[60:63]
	v_mfma_f32_16x16x32_bf16 v[60:63], v[132:135], v[148:151], v[60:63]
	v_mfma_f32_16x16x32_bf16 v[48:51], v[132:135], v[156:159], v[48:51]
	v_mfma_f32_16x16x32_bf16 v[48:51], v[128:131], v[152:155], v[48:51]
	v_mfma_f32_16x16x32_bf16 v[32:35], v[128:131], v[176:179], v[32:35]
	v_mfma_f32_16x16x32_bf16 v[32:35], v[132:135], v[180:183], v[32:35]
	v_mfma_f32_16x16x32_bf16 v[16:19], v[132:135], v[200:203], v[16:19]
	v_mfma_f32_16x16x32_bf16 v[16:19], v[128:131], v[196:199], v[16:19]
	v_mfma_f32_16x16x32_bf16 v[8:11], v[136:139], v[196:199], v[8:11]
	v_mfma_f32_16x16x32_bf16 v[8:11], v[140:143], v[200:203], v[8:11]
	v_mfma_f32_16x16x32_bf16 v[24:27], v[140:143], v[180:183], v[24:27]
	v_mfma_f32_16x16x32_bf16 v[24:27], v[136:139], v[176:179], v[24:27]
	v_mfma_f32_16x16x32_bf16 v[40:43], v[136:139], v[152:155], v[40:43]
	v_mfma_f32_16x16x32_bf16 v[40:43], v[140:143], v[156:159], v[40:43]
	v_mfma_f32_16x16x32_bf16 v[56:59], v[140:143], v[148:151], v[56:59]
	v_mfma_f32_16x16x32_bf16 v[56:59], v[136:139], v[144:147], v[56:59]
	s_setprio 0
	s_barrier
	s_add_u32 s22, s22, 0x100080
	s_addc_u32 s23, s23, 0
	s_add_i32 s24, s24, s34
	v_lshl_add_u64 v[128:129], s[22:23], 0, v[162:163]
	s_mov_b32 m0, s24
	s_nop 0
	global_load_lds_dwordx4 v[128:129], off
	v_lshl_add_u64 v[128:129], s[22:23], 0, v[166:167]
	s_add_i32 m0, s24, 0x2000
	s_nop 0
	global_load_lds_dwordx4 v[128:129], off
	s_waitcnt vmcnt(6)
	s_barrier
	s_setprio 1
	v_mfma_f32_16x16x32_bf16 v[52:55], v[204:207], v[144:147], v[52:55]
	v_mfma_f32_16x16x32_bf16 v[52:55], v[208:211], v[148:151], v[52:55]
	v_mfma_f32_16x16x32_bf16 v[36:39], v[208:211], v[156:159], v[36:39]
	v_mfma_f32_16x16x32_bf16 v[36:39], v[204:207], v[152:155], v[36:39]
	v_mfma_f32_16x16x32_bf16 v[20:23], v[204:207], v[176:179], v[20:23]
	v_mfma_f32_16x16x32_bf16 v[20:23], v[208:211], v[180:183], v[20:23]
	v_mfma_f32_16x16x32_bf16 v[4:7], v[208:211], v[200:203], v[4:7]
	v_mfma_f32_16x16x32_bf16 v[4:7], v[204:207], v[196:199], v[4:7]
	v_mfma_f32_16x16x32_bf16 v[0:3], v[212:215], v[196:199], v[0:3]
	v_mfma_f32_16x16x32_bf16 v[0:3], v[216:219], v[200:203], v[0:3]
	v_mfma_f32_16x16x32_bf16 v[12:15], v[216:219], v[180:183], v[12:15]
	v_mfma_f32_16x16x32_bf16 v[12:15], v[212:215], v[176:179], v[12:15]
	v_mfma_f32_16x16x32_bf16 v[28:31], v[212:215], v[152:155], v[28:31]
	v_mfma_f32_16x16x32_bf16 v[28:31], v[216:219], v[156:159], v[28:31]
	v_mfma_f32_16x16x32_bf16 v[44:47], v[216:219], v[148:151], v[44:47]
	v_mfma_f32_16x16x32_bf16 v[44:47], v[212:215], v[144:147], v[44:47]
	s_setprio 0
	s_add_i32 s46, s46, 2
	s_add_u32 s20, s20, 0x100
	s_addc_u32 s21, s21, 0
	s_add_u32 s11, s11, 0x100
	s_addc_u32 s13, s13, 0
	s_cmp_gt_u32 s46, 61
	s_barrier
	s_cbranch_scc0 .LBB0_522
	s_lshl_b32 s11, s18, 8
	v_lshl_or_b32 v128, s16, 8, v191
	v_add_u32_e32 v130, s11, v186
	v_ashrrev_i32_e32 v129, 31, v128
	v_ashrrev_i32_e32 v131, 31, v130
	v_lshl_add_u64 v[132:133], v[128:129], 1, s[6:7]
	v_lshlrev_b64 v[134:135], 11, v[130:131]
	v_lshl_add_u64 v[134:135], v[132:133], 0, v[134:135]
	global_load_dwordx4 v[198:201], v[134:135], off
	global_load_dwordx4 v[202:205], v[134:135], off offset:256
	v_or_b32_e32 v134, 16, v130
	v_ashrrev_i32_e32 v135, 31, v134
	v_lshlrev_b64 v[134:135], 11, v[134:135]
	v_lshl_add_u64 v[134:135], v[132:133], 0, v[134:135]
	global_load_dwordx4 v[206:209], v[134:135], off
	global_load_dwordx4 v[210:213], v[134:135], off offset:256
	v_or_b32_e32 v136, 32, v130
	v_ashrrev_i32_e32 v137, 31, v136
	v_or_b32_e32 v138, 48, v130
	v_add_u32_e32 v184, 0x80, v130
	v_add_u32_e32 v182, 0x90, v130
	v_add_u32_e32 v180, 0xa0, v130
	v_add_u32_e32 v178, 0xb0, v130
	v_lshlrev_b64 v[176:177], 2, v[128:129]
	v_lshlrev_b64 v[128:129], 12, v[130:131]
	v_lshlrev_b64 v[130:131], 11, v[136:137]
	v_lshl_add_u64 v[130:131], v[132:133], 0, v[130:131]
	global_load_dwordx4 v[214:217], v[130:131], off
	v_ashrrev_i32_e32 v139, 31, v138
	v_ashrrev_i32_e32 v185, 31, v184
	v_ashrrev_i32_e32 v183, 31, v182
	v_ashrrev_i32_e32 v181, 31, v180
	v_ashrrev_i32_e32 v179, 31, v178
	v_lshlrev_b64 v[134:135], 11, v[138:139]
	v_lshlrev_b64 v[136:137], 11, v[184:185]
	v_lshlrev_b64 v[138:139], 11, v[182:183]
	v_lshl_add_u32 v196, s45, 10, v192
	v_lshlrev_b64 v[140:141], 11, v[180:181]
	v_lshlrev_b64 v[142:143], 11, v[178:179]
	v_lshl_add_u64 v[128:129], s[26:27], 0, v[128:129]
	v_lshl_add_u64 v[134:135], v[132:133], 0, v[134:135]
	v_lshl_add_u64 v[136:137], v[132:133], 0, v[136:137]
	v_lshl_add_u64 v[138:139], v[132:133], 0, v[138:139]
	ds_read2_b32 v[230:231], v196 offset1:16
	v_lshl_add_u64 v[234:235], v[132:133], 0, v[140:141]
	v_lshl_add_u64 v[236:237], v[132:133], 0, v[142:143]
	v_lshl_add_u64 v[238:239], v[128:129], 0, v[176:177]
	global_load_dwordx4 v[218:221], v[130:131], off offset:256
	global_load_dwordx4 v[222:225], v[134:135], off
	global_load_dwordx4 v[226:229], v[134:135], off offset:256
	global_load_dwordx4 v[156:159], v[136:137], off
	global_load_dwordx4 v[152:155], v[136:137], off offset:256
	global_load_dwordx4 v[148:151], v[138:139], off
	global_load_dwordx4 v[144:147], v[138:139], off offset:256
	global_load_dwordx4 v[140:143], v[234:235], off
	s_nop 0
	global_load_dwordx4 v[136:139], v[234:235], off offset:256
	global_load_dwordx4 v[132:135], v[236:237], off
	global_load_dwordx4 v[128:131], v[236:237], off offset:256
	v_add_u32_e32 v232, s11, v188
	v_ashrrev_i32_e32 v233, 31, v232
	s_and_b64 vcc, exec, s[0:1]
	s_mov_b32 s16, s10
	s_mov_b32 s18, s12
	s_mov_b64 s[20:21], s[4:5]
	s_mov_b64 s[22:23], s[14:15]
	s_mov_b32 s45, s44
	s_waitcnt vmcnt(0)
; __device__ __forceinline__ float bf_lo(unsigned w) { return __uint_as_float(w << 16); }
; __device__ __forceinline__ float bf_hi(unsigned w) { return __uint_as_float(w & 0xffff0000u); }
;     __device__ __forceinline__ void operator()(const f32x4 (&acc)[2][2][4][2], const Unit& u, int ui, int wr, int wc, int fr, int fq) const {
;     ...
;         for (int ai = 0; ai < 2; ++ai)
; #pragma unroll
;             for (int m = 0; m < 4; ++m) { const int rl = rl0 + ai * 128 + m * 16; float* rowp = out + (size_t)(u.pm * 256 + rl) * DM + col0;
;                 const float r2 = tab[ui * 256 + rl];
; #pragma unroll
;                 for (int bj = 0; bj < 2; ++bj) { const u32x4 x = xv[ai][m][bj];
;                     const f32x4 x0 = {bf_lo(x.x), bf_hi(x.x), bf_lo(x.y), bf_hi(x.y)}, x1 = {bf_lo(x.z), bf_hi(x.z), bf_lo(x.w), bf_hi(x.w)};
;                     *(f32x4*)(rowp + bj * 128) = acc[ai][bj][m][0] * r2 + x0; *(f32x4*)(rowp + bj * 128 + 4) = acc[ai][bj][m][1] * r2 + x1; } }
	v_lshlrev_b32_e32 v234, 16, v198
	v_and_b32_e32 v235, 0xffff0000, v198
	v_lshlrev_b32_e32 v198, 16, v199
	v_and_b32_e32 v199, 0xffff0000, v199
	v_lshlrev_b32_e32 v242, 16, v204
	v_and_b32_e32 v243, 0xffff0000, v204
	v_lshlrev_b32_e32 v236, 16, v200
	v_and_b32_e32 v237, 0xffff0000, v200
	v_lshlrev_b32_e32 v200, 16, v201
	v_and_b32_e32 v201, 0xffff0000, v201
	v_lshlrev_b32_e32 v240, 16, v202
	v_and_b32_e32 v241, 0xffff0000, v202
	v_lshlrev_b32_e32 v202, 16, v203
	v_and_b32_e32 v203, 0xffff0000, v203
	v_lshlrev_b32_e32 v204, 16, v205
	v_and_b32_e32 v205, 0xffff0000, v205
	s_waitcnt lgkmcnt(0)
	v_pk_fma_f32 v[126:127], v[126:127], v[230:231], v[198:199] op_sel_hi:[1,0,1]
	v_pk_fma_f32 v[124:125], v[124:125], v[230:231], v[234:235] op_sel_hi:[1,0,1]
	v_pk_fma_f32 v[108:109], v[108:109], v[230:231], v[242:243] op_sel_hi:[1,0,1]
	v_pk_fma_f32 v[122:123], v[122:123], v[230:231], v[200:201] op_sel_hi:[1,0,1]
	v_pk_fma_f32 v[120:121], v[120:121], v[230:231], v[236:237] op_sel_hi:[1,0,1]
	v_pk_fma_f32 v[118:119], v[118:119], v[230:231], v[202:203] op_sel_hi:[1,0,1]
	v_pk_fma_f32 v[116:117], v[116:117], v[230:231], v[240:241] op_sel_hi:[1,0,1]
	v_pk_fma_f32 v[110:111], v[110:111], v[230:231], v[204:205] op_sel_hi:[1,0,1]
	global_store_dwordx4 v[238:239], v[124:127], off
	global_store_dwordx4 v[238:239], v[120:123], off offset:16
	global_store_dwordx4 v[238:239], v[116:119], off offset:512
	global_store_dwordx4 v[238:239], v[108:111], off offset:528
	v_mov_b32_e32 v122, v231
	v_lshlrev_b32_e32 v118, 16, v208
	v_lshlrev_b64 v[108:109], 12, v[232:233]
	v_lshl_add_u64 v[108:109], s[26:27], 0, v[108:109]
	v_lshl_add_u64 v[116:117], v[108:109], 0, v[176:177]
	v_lshlrev_b32_e32 v108, 16, v206
	v_and_b32_e32 v109, 0xffff0000, v206
	v_lshlrev_b32_e32 v110, 16, v207
	v_and_b32_e32 v111, 0xffff0000, v207
	v_pk_fma_f32 v[110:111], v[114:115], v[122:123], v[110:111] op_sel_hi:[1,0,1]
	v_pk_fma_f32 v[108:109], v[112:113], v[122:123], v[108:109] op_sel_hi:[1,0,1]
	global_store_dwordx4 v[116:117], v[108:111], off
	v_and_b32_e32 v119, 0xffff0000, v208
	v_lshlrev_b32_e32 v120, 16, v209
	v_lshlrev_b32_e32 v108, 16, v212
	v_and_b32_e32 v109, 0xffff0000, v212
	v_lshlrev_b32_e32 v110, 16, v213
	v_and_b32_e32 v111, 0xffff0000, v213
	v_pk_fma_f32 v[98:99], v[98:99], v[122:123], v[110:111] op_sel_hi:[1,0,1]
	v_pk_fma_f32 v[96:97], v[96:97], v[122:123], v[108:109] op_sel_hi:[1,0,1]
	v_and_b32_e32 v121, 0xffff0000, v209
	global_store_dwordx4 v[116:117], v[96:99], off offset:528
	ds_read2_b32 v[98:99], v196 offset0:32 offset1:48
	v_pk_fma_f32 v[106:107], v[106:107], v[122:123], v[120:121] op_sel_hi:[1,0,1]
	v_pk_fma_f32 v[104:105], v[104:105], v[122:123], v[118:119] op_sel_hi:[1,0,1]
	v_add_u32_e32 v96, s11, v189
	global_store_dwordx4 v[116:117], v[104:107], off offset:16
	v_ashrrev_i32_e32 v97, 31, v96
	v_lshlrev_b64 v[96:97], 12, v[96:97]
	v_lshlrev_b32_e32 v104, 16, v210
	v_and_b32_e32 v105, 0xffff0000, v210
	v_lshlrev_b32_e32 v106, 16, v211
	v_and_b32_e32 v107, 0xffff0000, v211
	v_pk_fma_f32 v[102:103], v[102:103], v[122:123], v[106:107] op_sel_hi:[1,0,1]
	v_pk_fma_f32 v[100:101], v[100:101], v[122:123], v[104:105] op_sel_hi:[1,0,1]
	global_store_dwordx4 v[116:117], v[100:103], off offset:512
	v_lshl_add_u64 v[96:97], s[26:27], 0, v[96:97]
	v_lshl_add_u64 v[96:97], v[96:97], 0, v[176:177]
	v_lshlrev_b32_e32 v100, 16, v214
	v_and_b32_e32 v101, 0xffff0000, v214
	v_lshlrev_b32_e32 v102, 16, v215
	v_and_b32_e32 v103, 0xffff0000, v215
	s_waitcnt lgkmcnt(0)
	v_pk_fma_f32 v[94:95], v[94:95], v[98:99], v[102:103] op_sel_hi:[1,0,1]
	v_pk_fma_f32 v[92:93], v[92:93], v[98:99], v[100:101] op_sel_hi:[1,0,1]
	global_store_dwordx4 v[96:97], v[92:95], off
	v_lshlrev_b32_e32 v104, 16, v216
	v_and_b32_e32 v105, 0xffff0000, v216
	v_lshlrev_b32_e32 v92, 16, v220
	v_and_b32_e32 v93, 0xffff0000, v220
	v_lshlrev_b32_e32 v94, 16, v221
	v_and_b32_e32 v95, 0xffff0000, v221
	v_lshlrev_b32_e32 v106, 16, v217
	v_and_b32_e32 v107, 0xffff0000, v217
	v_pk_fma_f32 v[82:83], v[82:83], v[98:99], v[94:95] op_sel_hi:[1,0,1]
	v_pk_fma_f32 v[80:81], v[80:81], v[98:99], v[92:93] op_sel_hi:[1,0,1]
	v_pk_fma_f32 v[90:91], v[90:91], v[98:99], v[106:107] op_sel_hi:[1,0,1]
	v_pk_fma_f32 v[88:89], v[88:89], v[98:99], v[104:105] op_sel_hi:[1,0,1]
	global_store_dwordx4 v[96:97], v[80:83], off offset:528
	global_store_dwordx4 v[96:97], v[88:91], off offset:16
	s_nop 0
	v_add_u32_e32 v80, s11, v190
	v_lshlrev_b32_e32 v88, 16, v218
	v_and_b32_e32 v89, 0xffff0000, v218
	v_lshlrev_b32_e32 v90, 16, v219
	v_and_b32_e32 v91, 0xffff0000, v219
	v_ashrrev_i32_e32 v81, 31, v80
	v_pk_fma_f32 v[86:87], v[86:87], v[98:99], v[90:91] op_sel_hi:[1,0,1]
	v_pk_fma_f32 v[84:85], v[84:85], v[98:99], v[88:89] op_sel_hi:[1,0,1]
	v_lshlrev_b64 v[80:81], 12, v[80:81]
	global_store_dwordx4 v[96:97], v[84:87], off offset:512
	v_lshl_add_u64 v[80:81], s[26:27], 0, v[80:81]
	v_lshlrev_b32_e32 v82, 16, v222
	v_and_b32_e32 v83, 0xffff0000, v222
	v_lshlrev_b32_e32 v84, 16, v223
	v_and_b32_e32 v85, 0xffff0000, v223
	v_mov_b32_e32 v90, v99
	v_lshl_add_u64 v[80:81], v[80:81], 0, v[176:177]
	v_pk_fma_f32 v[78:79], v[78:79], v[90:91], v[84:85] op_sel_hi:[1,0,1]
	v_pk_fma_f32 v[76:77], v[76:77], v[90:91], v[82:83] op_sel_hi:[1,0,1]
	global_store_dwordx4 v[80:81], v[76:79], off
	v_lshlrev_b32_e32 v86, 16, v224
	v_and_b32_e32 v87, 0xffff0000, v224
	v_lshlrev_b32_e32 v76, 16, v228
	v_and_b32_e32 v77, 0xffff0000, v228
	v_lshlrev_b32_e32 v78, 16, v229
	v_and_b32_e32 v79, 0xffff0000, v229
	v_pk_fma_f32 v[66:67], v[66:67], v[90:91], v[78:79] op_sel_hi:[1,0,1]
	v_pk_fma_f32 v[64:65], v[64:65], v[90:91], v[76:77] op_sel_hi:[1,0,1]
	v_lshlrev_b32_e32 v88, 16, v225
	v_and_b32_e32 v89, 0xffff0000, v225
	global_store_dwordx4 v[80:81], v[64:67], off offset:528
	ds_read2_b32 v[66:67], v196 offset0:128 offset1:144
	v_pk_fma_f32 v[74:75], v[74:75], v[90:91], v[88:89] op_sel_hi:[1,0,1]
	v_pk_fma_f32 v[72:73], v[72:73], v[90:91], v[86:87] op_sel_hi:[1,0,1]
	global_store_dwordx4 v[80:81], v[72:75], off offset:16
	v_lshlrev_b64 v[64:65], 12, v[184:185]
	v_lshl_add_u64 v[64:65], s[26:27], 0, v[64:65]
	v_lshlrev_b32_e32 v72, 16, v226
	v_and_b32_e32 v73, 0xffff0000, v226
	v_lshlrev_b32_e32 v74, 16, v227
	v_and_b32_e32 v75, 0xffff0000, v227
	v_pk_fma_f32 v[70:71], v[70:71], v[90:91], v[74:75] op_sel_hi:[1,0,1]
	v_pk_fma_f32 v[68:69], v[68:69], v[90:91], v[72:73] op_sel_hi:[1,0,1]
	global_store_dwordx4 v[80:81], v[68:71], off offset:512
	v_lshl_add_u64 v[64:65], v[64:65], 0, v[176:177]
	v_lshlrev_b32_e32 v72, 16, v158
	v_lshlrev_b32_e32 v68, 16, v156
	v_and_b32_e32 v69, 0xffff0000, v156
	v_lshlrev_b32_e32 v70, 16, v157
	v_and_b32_e32 v71, 0xffff0000, v157
	v_and_b32_e32 v73, 0xffff0000, v158
	v_lshlrev_b32_e32 v74, 16, v159
	v_and_b32_e32 v75, 0xffff0000, v159
	s_waitcnt lgkmcnt(0)
; __device__ __forceinline__ float bf_lo(unsigned w) { return __uint_as_float(w << 16); }
; __device__ __forceinline__ float bf_hi(unsigned w) { return __uint_as_float(w & 0xffff0000u); }
; #define PG8_WAIT_V(n) asm volatile("s_waitcnt vmcnt(" #n ")" ::: "memory")
; #define PG8_BAR __builtin_amdgcn_s_barrier()
; template <class Epi, class Ptrs>
; __device__ __forceinline__ void gemm_phase(LAS unsigned char* lds, const int K, const StaticOrder& S, const Ptrs& P, const Epi& E) {
;     ...
;         if (!has_next) break;
; #pragma unroll
;         for (int a = 0; a < 2; ++a)
; #pragma unroll
;             for (int b = 0; b < 2; ++b)
; #pragma unroll
;                 for (int m = 0; m < 4; ++m)
; #pragma unroll
;                     for (int n = 0; n < 2; ++n) acc[a][b][m][n] = (f32x4){0.f, 0.f, 0.f, 0.f};
;         cur = nxt; cA = nA; cB = nB; ++ui;
;     }
;     PG8_WAIT_V(0);
;     if (wr == 0) PG8_BAR;
;     PG8_BAR;
;     __device__ __forceinline__ void operator()(const f32x4 (&acc)[2][2][4][2], const Unit& u, int ui, int wr, int wc, int fr, int fq) const {
;     ...
;         for (int ai = 0; ai < 2; ++ai)
; #pragma unroll
;             for (int m = 0; m < 4; ++m) { const int rl = rl0 + ai * 128 + m * 16; float* rowp = out + (size_t)(u.pm * 256 + rl) * DM + col0;
;                 const float r2 = tab[ui * 256 + rl];
; #pragma unroll
;                 for (int bj = 0; bj < 2; ++bj) { const u32x4 x = xv[ai][m][bj];
;                     const f32x4 x0 = {bf_lo(x.x), bf_hi(x.x), bf_lo(x.y), bf_hi(x.y)}, x1 = {bf_lo(x.z), bf_hi(x.z), bf_lo(x.w), bf_hi(x.w)};
;                     *(f32x4*)(rowp + bj * 128) = acc[ai][bj][m][0] * r2 + x0; *(f32x4*)(rowp + bj * 128 + 4) = acc[ai][bj][m][1] * r2 + x1; } }
	v_pk_fma_f32 v[62:63], v[62:63], v[66:67], v[70:71] op_sel_hi:[1,0,1]
	v_pk_fma_f32 v[60:61], v[60:61], v[66:67], v[68:69] op_sel_hi:[1,0,1]
	global_store_dwordx4 v[64:65], v[60:63], off
	v_pk_fma_f32 v[58:59], v[58:59], v[66:67], v[74:75] op_sel_hi:[1,0,1]
	v_pk_fma_f32 v[56:57], v[56:57], v[66:67], v[72:73] op_sel_hi:[1,0,1]
	v_lshlrev_b32_e32 v60, 16, v154
	v_and_b32_e32 v61, 0xffff0000, v154
	v_lshlrev_b32_e32 v62, 16, v155
	v_and_b32_e32 v63, 0xffff0000, v155
	global_store_dwordx4 v[64:65], v[56:59], off offset:16
	v_pk_fma_f32 v[46:47], v[46:47], v[66:67], v[62:63] op_sel_hi:[1,0,1]
	v_pk_fma_f32 v[44:45], v[44:45], v[66:67], v[60:61] op_sel_hi:[1,0,1]
	v_lshlrev_b32_e32 v56, 16, v152
	v_and_b32_e32 v57, 0xffff0000, v152
	v_lshlrev_b32_e32 v58, 16, v153
	v_and_b32_e32 v59, 0xffff0000, v153
	v_pk_fma_f32 v[54:55], v[54:55], v[66:67], v[58:59] op_sel_hi:[1,0,1]
	v_pk_fma_f32 v[52:53], v[52:53], v[66:67], v[56:57] op_sel_hi:[1,0,1]
	global_store_dwordx4 v[64:65], v[44:47], off offset:528
	global_store_dwordx4 v[64:65], v[52:55], off offset:512
	v_lshlrev_b32_e32 v56, 16, v151
	v_lshlrev_b64 v[44:45], 12, v[182:183]
	v_lshl_add_u64 v[44:45], s[26:27], 0, v[44:45]
	v_lshlrev_b32_e32 v54, 16, v150
	v_and_b32_e32 v55, 0xffff0000, v150
	v_and_b32_e32 v57, 0xffff0000, v151
	v_mov_b32_e32 v58, v67
	v_lshl_add_u64 v[52:53], v[44:45], 0, v[176:177]
	v_pk_fma_f32 v[42:43], v[42:43], v[58:59], v[56:57] op_sel_hi:[1,0,1]
	v_pk_fma_f32 v[40:41], v[40:41], v[58:59], v[54:55] op_sel_hi:[1,0,1]
	v_lshlrev_b32_e32 v44, 16, v148
	v_and_b32_e32 v45, 0xffff0000, v148
	v_lshlrev_b32_e32 v46, 16, v149
	v_and_b32_e32 v47, 0xffff0000, v149
	global_store_dwordx4 v[52:53], v[40:43], off offset:16
	v_pk_fma_f32 v[46:47], v[50:51], v[58:59], v[46:47] op_sel_hi:[1,0,1]
	v_pk_fma_f32 v[44:45], v[48:49], v[58:59], v[44:45] op_sel_hi:[1,0,1]
	v_lshlrev_b32_e32 v40, 16, v144
	v_and_b32_e32 v41, 0xffff0000, v144
	v_lshlrev_b32_e32 v42, 16, v145
	v_and_b32_e32 v43, 0xffff0000, v145
	v_pk_fma_f32 v[38:39], v[38:39], v[58:59], v[42:43] op_sel_hi:[1,0,1]
	v_pk_fma_f32 v[36:37], v[36:37], v[58:59], v[40:41] op_sel_hi:[1,0,1]
	global_store_dwordx4 v[52:53], v[44:47], off
	global_store_dwordx4 v[52:53], v[36:39], off offset:512
	ds_read2_b32 v[38:39], v196 offset0:160 offset1:176
	v_lshlrev_b32_e32 v44, 16, v146
	v_and_b32_e32 v45, 0xffff0000, v146
	v_lshlrev_b32_e32 v46, 16, v147
	v_and_b32_e32 v47, 0xffff0000, v147
	v_pk_fma_f32 v[30:31], v[30:31], v[58:59], v[46:47] op_sel_hi:[1,0,1]
	v_pk_fma_f32 v[28:29], v[28:29], v[58:59], v[44:45] op_sel_hi:[1,0,1]
	global_store_dwordx4 v[52:53], v[28:31], off offset:528
	v_lshlrev_b32_e32 v40, 16, v142
	v_and_b32_e32 v41, 0xffff0000, v142
	v_lshlrev_b64 v[28:29], 12, v[180:181]
	v_lshl_add_u64 v[28:29], s[26:27], 0, v[28:29]
	v_lshl_add_u64 v[36:37], v[28:29], 0, v[176:177]
	v_lshlrev_b32_e32 v28, 16, v140
	v_and_b32_e32 v29, 0xffff0000, v140
	v_lshlrev_b32_e32 v30, 16, v141
	v_and_b32_e32 v31, 0xffff0000, v141
	s_waitcnt lgkmcnt(0)
	v_pk_fma_f32 v[30:31], v[34:35], v[38:39], v[30:31] op_sel_hi:[1,0,1]
	v_pk_fma_f32 v[28:29], v[32:33], v[38:39], v[28:29] op_sel_hi:[1,0,1]
	v_lshlrev_b32_e32 v42, 16, v143
	v_and_b32_e32 v43, 0xffff0000, v143
	global_store_dwordx4 v[36:37], v[28:31], off
	v_pk_fma_f32 v[26:27], v[26:27], v[38:39], v[42:43] op_sel_hi:[1,0,1]
	v_pk_fma_f32 v[24:25], v[24:25], v[38:39], v[40:41] op_sel_hi:[1,0,1]
	v_lshlrev_b32_e32 v28, 16, v138
	v_and_b32_e32 v29, 0xffff0000, v138
	v_lshlrev_b32_e32 v30, 16, v139
	v_and_b32_e32 v31, 0xffff0000, v139
	v_pk_fma_f32 v[14:15], v[14:15], v[38:39], v[30:31] op_sel_hi:[1,0,1]
	v_pk_fma_f32 v[12:13], v[12:13], v[38:39], v[28:29] op_sel_hi:[1,0,1]
	global_store_dwordx4 v[36:37], v[24:27], off offset:16
	global_store_dwordx4 v[36:37], v[12:15], off offset:528
	s_nop 0
	v_lshlrev_b32_e32 v24, 16, v136
	v_and_b32_e32 v25, 0xffff0000, v136
	v_lshlrev_b32_e32 v26, 16, v137
	v_and_b32_e32 v27, 0xffff0000, v137
	v_lshlrev_b64 v[12:13], 12, v[178:179]
	v_pk_fma_f32 v[22:23], v[22:23], v[38:39], v[26:27] op_sel_hi:[1,0,1]
	v_pk_fma_f32 v[20:21], v[20:21], v[38:39], v[24:25] op_sel_hi:[1,0,1]
	v_lshl_add_u64 v[12:13], s[26:27], 0, v[12:13]
	global_store_dwordx4 v[36:37], v[20:23], off offset:512
	v_lshlrev_b32_e32 v14, 16, v133
	v_and_b32_e32 v15, 0xffff0000, v133
	v_lshl_add_u64 v[20:21], v[12:13], 0, v[176:177]
	v_lshlrev_b32_e32 v12, 16, v132
	v_and_b32_e32 v13, 0xffff0000, v132
	v_lshlrev_b32_e32 v22, 16, v134
	v_and_b32_e32 v23, 0xffff0000, v134
	v_lshlrev_b32_e32 v24, 16, v135
	v_and_b32_e32 v25, 0xffff0000, v135
	v_mov_b32_e32 v26, v39
	v_pk_fma_f32 v[14:15], v[18:19], v[26:27], v[14:15] op_sel_hi:[1,0,1]
	v_pk_fma_f32 v[12:13], v[16:17], v[26:27], v[12:13] op_sel_hi:[1,0,1]
	v_pk_fma_f32 v[10:11], v[10:11], v[26:27], v[24:25] op_sel_hi:[1,0,1]
	v_pk_fma_f32 v[8:9], v[8:9], v[26:27], v[22:23] op_sel_hi:[1,0,1]
	global_store_dwordx4 v[20:21], v[12:15], off
	global_store_dwordx4 v[20:21], v[8:11], off offset:16
	s_nop 0
	v_lshlrev_b32_e32 v12, 16, v130
	v_lshlrev_b32_e32 v8, 16, v128
	v_and_b32_e32 v9, 0xffff0000, v128
	v_lshlrev_b32_e32 v10, 16, v129
	v_and_b32_e32 v11, 0xffff0000, v129
	v_and_b32_e32 v13, 0xffff0000, v130
	v_lshlrev_b32_e32 v14, 16, v131
	v_and_b32_e32 v15, 0xffff0000, v131
	v_pk_fma_f32 v[6:7], v[6:7], v[26:27], v[10:11] op_sel_hi:[1,0,1]
	v_pk_fma_f32 v[4:5], v[4:5], v[26:27], v[8:9] op_sel_hi:[1,0,1]
	v_pk_fma_f32 v[2:3], v[2:3], v[26:27], v[14:15] op_sel_hi:[1,0,1]
	v_pk_fma_f32 v[0:1], v[0:1], v[26:27], v[12:13] op_sel_hi:[1,0,1]
	global_store_dwordx4 v[20:21], v[4:7], off offset:512
	global_store_dwordx4 v[20:21], v[0:3], off offset:528
	s_cbranch_vccz .LBB0_517
	s_waitcnt vmcnt(0)
	s_cmpk_gt_u32 s33, 0xff
	s_cbranch_scc1 .LBB0_526
	s_barrier
